# removed the P5/P11 XCD stagger (it cost 30us per phase); P7 E waves: row-group scan of gate products via v_permlane16/32_swap instead of 4 ds_bpermute rounds; M waves post-barrier sleep retuned to 13
# baseline (speedup 1.0000x reference)
; #define LAS __attribute__((address_space(3)))
;     ...
;     const LAS unsigned char* qrow = base + OFF_Q + (16 * ti + l16) * QS + kq * 16;
;     const LAS unsigned char* krow = base + OFF_K + l16 * QS + kq * 16;
;     const LAS unsigned char* srow = lds + OFF_ST + SET * ST_BYTES + l16 * QS + kq * 16;
;     const LAS unsigned char* vrow = base + OFF_VT + l16 * TS;
; #pragma unroll
;     for (int kk = 0; kk < 4; ++kk) { qf[kk] = *(const LAS bf16x8*)(qrow + kk * 64); sb[0][kk] = *(const LAS bf16x8*)(srow + kk * 64); sb[1][kk] = *(const LAS bf16x8*)(srow + 16 * QS + kk * 64); }
; #pragma unroll
;     for (int si = 0; si < 4; ++si)
; #pragma unroll
;         for (int kk = 0; kk < 4; ++kk) kf[si][kk] = *(const LAS bf16x8*)(krow + si * 16 * QS + kk * 64);
; #pragma unroll
;     for (int vh = 0; vh < 2; ++vh)
; #pragma unroll
;         for (int p = 0; p < 2; ++p) { va[vh][p] = *(const LAS u32x2*)(vrow + vh * 16 * TS + kq * 8 + p * 64); vb2[vh][p] = *(const LAS u32x2*)(vrow + vh * 16 * TS + kq * 8 + p * 64 + 32); }
; #pragma unroll
;     for (int kk = 0; kk < 2; ++kk) { vv[0][kk] = *(const LAS bf16x8*)(vrow + kk * 64 + kq * 16); vv[1][kk] = *(const LAS bf16x8*)(vrow + 16 * TS + kk * 64 + kq * 16);
;         kt[0][kk] = *(const LAS bf16x8*)(base + OFF_KT + (32 * ti + l16) * TS + kk * 64 + kq * 16); kt[1][kk] = *(const LAS bf16x8*)(base + OFF_KT + (32 * ti + 16 + l16) * TS + kk * 64 + kq * 16); }
;     dl[0] = *(const LAS f32x4*)(base + OFF_DL + (32 * ti + 4 * kq) * 4); dl[1] = *(const LAS f32x4*)(base + OFF_DL + (32 * ti + 16 + 4 * kq) * 4);
;     __builtin_amdgcn_sched_barrier(0);
;     f32x4 o[2], as[4];
;     o[0] = (f32x4){0.f, 0.f, 0.f, 0.f}; o[1] = o[0];
; #pragma unroll
;     for (int si = 0; si < 4; ++si) as[si] = (f32x4){0.f, 0.f, 0.f, 0.f};
; #pragma unroll
;     for (int kk = 0; kk < 4; ++kk) { o[0] = MFMA16(qf[kk], sb[0][kk], o[0]); o[1] = MFMA16(qf[kk], sb[1][kk], o[1]);
; #pragma unroll
;         for (int si = 0; si < 4; ++si) as[si] = MFMA16(kf[si][kk], qf[kk], as[si]); }
; #pragma unroll
;     for (int ds = 0; ds < 2; ++ds)
; #pragma unroll
;         for (int vh = 0; vh < 2; ++vh) { st[ds][vh] = st[ds][vh] * dl[ds];
; #pragma unroll
;             for (int kk = 0; kk < 2; ++kk) st[ds][vh] = MFMA16(kt[ds][kk], vv[vh][kk], st[ds][vh]); }
;     const int tq = 16 * ti + l16 - 4 * kq;
; #pragma unroll
;     for (int si = 0; si < 4; ++si)
; #pragma unroll
.LBB0_1179:
	v_add_u32_e32 v28, v117, v84
	ds_read_b128 v[100:103], v99
	ds_read_b128 v[104:107], v99 offset:64
	ds_read_b128 v[108:111], v28
	ds_read_b128 v[138:141], v28 offset:64
	ds_read_b128 v[142:145], v28 offset:4352
	ds_read_b128 v[146:149], v28 offset:4416
	ds_read_b128 v[48:51], v99 offset:128
	ds_read_b128 v[24:27], v99 offset:192
	ds_read_b128 v[56:59], v28 offset:128
	ds_read_b128 v[32:35], v28 offset:192
	ds_read_b128 v[150:153], v28 offset:4480
	ds_read_b128 v[52:55], v28 offset:4544
	v_add_u32_e32 v28, v116, v84
	ds_read_b128 v[154:157], v28 offset:17408
	ds_read_b128 v[158:161], v28 offset:17472
	ds_read_b128 v[162:165], v28 offset:17536
	ds_read_b128 v[60:63], v28 offset:17600
	ds_read_b128 v[166:169], v28 offset:21760
	ds_read_b128 v[170:173], v28 offset:21824
	ds_read_b128 v[174:177], v28 offset:21888
	ds_read_b128 v[64:67], v28 offset:21952
	ds_read_b128 v[178:181], v28 offset:26112
	ds_read_b128 v[182:185], v28 offset:26176
	ds_read_b128 v[186:189], v28 offset:26240
	ds_read_b128 v[68:71], v28 offset:26304
	ds_read_b128 v[190:193], v28 offset:30464
	ds_read_b128 v[194:197], v28 offset:30528
	ds_read_b128 v[76:79], v28 offset:30592
	ds_read_b128 v[72:75], v28 offset:30656
	v_add_u32_e32 v36, v118, v119
	v_add_u32_e32 v28, 0xd000, v36
	v_add_u32_e32 v36, 0xd800, v36
	v_add_u32_e32 v112, v118, v84
	ds_read2_b64 v[40:43], v28 offset1:4
	ds_read2_b64 v[28:31], v28 offset0:8 offset1:12
	ds_read2_b64 v[44:47], v36 offset0:32 offset1:36
	ds_read2_b64 v[36:39], v36 offset0:40 offset1:44
	v_add_u32_e32 v113, v115, v89
	ds_read_b128 v[202:205], v112 offset:53248
	ds_read_b128 v[208:211], v112 offset:53312
	ds_read_b128 v[212:215], v112 offset:55552
	ds_read_b128 v[216:219], v112 offset:55616
	ds_read_b128 v[220:223], v113 offset:34816
	ds_read_b128 v[224:227], v113 offset:34880
	ds_read_b128 v[228:231], v113 offset:37120
	ds_read_b128 v[232:235], v113 offset:37184
	ds_read_b128 v[236:239], v95 offset:57856
	ds_read_b128 v[240:243], v95 offset:57920
	s_add_i32 s3, s3, 2
	s_waitcnt lgkmcnt(14)
	v_mfma_f32_16x16x32_bf16 v[142:145], v[142:145], v[100:103], 0
	s_waitcnt lgkmcnt(1)
	v_pk_mul_f32 v[20:21], v[20:21], v[236:237]
	v_pk_mul_f32 v[22:23], v[22:23], v[238:239]
	v_pk_mul_f32 v[8:9], v[8:9], v[236:237]
	v_mfma_f32_16x16x32_bf16 v[154:157], v[154:157], v[100:103], 0
	v_mul_f32_e64 v10, v10, v238
	v_mul_f32_e64 v11, v11, v239
	s_waitcnt lgkmcnt(0)
	v_pk_mul_f32 v[16:17], v[16:17], v[240:241]
	v_pk_mul_f32 v[18:19], v[18:19], v[242:243]
	v_mfma_f32_16x16x32_bf16 v[166:169], v[166:169], v[100:103], 0
	v_mul_f32_e64 v12, v12, v240
	v_mul_f32_e64 v13, v13, v241
	v_pk_mul_f32 v[14:15], v[14:15], v[242:243]
	s_movk_i32 s0, 0x1000
	v_mfma_f32_16x16x32_bf16 v[178:181], v[178:181], v[100:103], 0
	v_add_co_u32_e32 v112, vcc, s0, v92
	s_movk_i32 s0, 0x3000
	v_mfma_f32_16x16x32_bf16 v[190:193], v[190:193], v[100:103], 0
	v_addc_co_u32_e32 v113, vcc, 0, v93, vcc
	v_mfma_f32_16x16x32_bf16 v[100:103], v[108:111], v[100:103], 0
	v_mfma_f32_16x16x32_bf16 v[108:111], v[220:223], v[212:215], v[20:23]
	v_mfma_f32_16x16x32_bf16 v[142:145], v[146:149], v[104:107], v[142:145]
	v_mfma_f32_16x16x32_bf16 v[146:149], v[158:161], v[104:107], v[154:157]
	v_mfma_f32_16x16x32_bf16 v[154:157], v[170:173], v[104:107], v[166:169]
	v_mfma_f32_16x16x32_bf16 v[8:11], v[220:223], v[202:205], v[8:11]
	v_mfma_f32_16x16x32_bf16 v[202:205], v[228:231], v[202:205], v[16:19]
	v_mfma_f32_16x16x32_bf16 v[158:161], v[182:185], v[104:107], v[178:181]
	v_mfma_f32_16x16x32_bf16 v[166:169], v[194:197], v[104:107], v[190:193]
	v_mfma_f32_16x16x32_bf16 v[100:103], v[138:141], v[104:107], v[100:103]
	v_mfma_f32_16x16x32_bf16 v[16:19], v[224:227], v[216:219], v[108:111]
	v_mfma_f32_16x16x32_bf16 v[108:111], v[162:165], v[48:51], v[146:149]
	v_mfma_f32_16x16x32_bf16 v[138:141], v[174:177], v[48:51], v[154:157]
	s_nop 1
	v_add_co_u32_e32 v146, vcc, s67, v92
	v_mfma_f32_16x16x32_bf16 v[212:215], v[228:231], v[212:215], v[12:15]
	s_nop 0
	v_addc_co_u32_e32 v147, vcc, 0, v93, vcc
	v_add_co_u32_e32 v148, vcc, s0, v92
	v_mfma_f32_16x16x32_bf16 v[104:107], v[150:153], v[48:51], v[142:145]
	v_add_u32_e32 v152, v121, v94
	s_min_u32 s0, s3, 0x7c
	s_lshl_b32 s48, s0, 18
	v_mfma_f32_16x16x32_bf16 v[142:145], v[186:189], v[48:51], v[158:161]
	v_addc_co_u32_e32 v149, vcc, 0, v93, vcc
	v_lshl_add_u64 v[150:151], v[90:91], 0, s[48:49]
	v_mfma_f32_16x16x32_bf16 v[76:79], v[76:79], v[48:51], v[166:169]
	s_mov_b32 s0, 0xc0000
	v_add_co_u32_e32 v150, vcc, s0, v150
	v_mfma_f32_16x16x32_bf16 v[48:51], v[56:59], v[48:51], v[100:103]
	s_nop 0
	v_addc_co_u32_e32 v151, vcc, 0, v151, vcc
	v_mfma_f32_16x16x32_bf16 v[56:59], v[60:63], v[24:27], v[108:111]
	v_cvt_pk_bf16_f32 v102, v16, v17
	v_cvt_pk_bf16_f32 v103, v18, v19
	v_mfma_f32_16x16x32_bf16 v[60:63], v[64:67], v[24:27], v[138:141]
	v_mfma_f32_16x16x32_bf16 v[20:23], v[224:227], v[208:211], v[8:11]
	s_nop 3
	v_cndmask_b32_e64 v58, v58, 0, s[20:21]
	s_nop 1
	v_cndmask_b32_e64 v62, v62, 0, s[28:29]
	v_cndmask_b32_e64 v60, v60, 0, s[24:25]
	v_mfma_f32_16x16x32_bf16 v[8:11], v[232:235], v[216:219], v[212:215]
	v_cndmask_b32_e64 v56, v56, 0, s[64:65]
	v_cvt_pk_bf16_f32 v100, v20, v21
	v_cvt_pk_bf16_f32 v101, v22, v23
	v_mfma_f32_16x16x32_bf16 v[52:55], v[52:55], v[24:27], v[104:107]
	v_mfma_f32_16x16x32_bf16 v[64:67], v[68:71], v[24:27], v[142:145]
	s_nop 2
	v_cvt_pk_bf16_f32 v106, v8, v9
	v_cvt_pk_bf16_f32 v107, v10, v11
	v_mfma_f32_16x16x32_bf16 v[68:71], v[72:75], v[24:27], v[76:79]
	v_mfma_f32_16x16x32_bf16 v[24:27], v[32:35], v[24:27], v[48:51]
	v_cndmask_b32_e64 v35, v63, 0, s[30:31]
	v_cndmask_b32_e64 v34, v61, 0, s[26:27]
	v_cndmask_b32_e64 v33, v59, 0, s[22:23]
	v_cndmask_b32_e64 v32, v57, 0, s[16:17]
	v_mfma_f32_16x16x32_bf16 v[12:15], v[232:235], v[208:211], v[202:205]
	v_cvt_pk_bf16_f32 v32, v56, v32
	v_cvt_pk_bf16_f32 v33, v58, v33
	v_cvt_pk_bf16_f32 v34, v60, v34
	v_cvt_pk_bf16_f32 v35, v62, v35
	v_cndmask_b32_e64 v48, v69, 0, s[44:45]
	s_nop 2
	v_cvt_pk_bf16_f32 v104, v12, v13
	v_cvt_pk_bf16_f32 v105, v14, v15
	ds_write_b64 v152, v[100:101]
	ds_write_b64 v152, v[102:103] offset:4352
	ds_write_b64 v96, v[104:105]
	ds_write_b64 v96, v[106:107] offset:4352
	s_waitcnt vmcnt(3)
; __device__ __forceinline__ unsigned cvtpk_s(float lo, float hi) { f32x2_t v = {lo, hi}; bf16x2_t b = __builtin_convertvector(v, bf16x2_t); return __builtin_bit_cast(unsigned, b); }
; #define HBAR() do { asm volatile("s_waitcnt lgkmcnt(0)" ::: "memory"); __builtin_amdgcn_s_barrier(); asm volatile("" ::: "memory"); } while (0)
; #define MFMA16(a, b, c) __builtin_amdgcn_mfma_f32_16x16x32_bf16((a), (b), (c), 0, 0, 0)
;     ...
;     for (int p = 0; p < 2; ++p) {
;         u32x4 pw; pw.x = cvtpk_s(as[2 * p][0], as[2 * p][1]); pw.y = cvtpk_s(as[2 * p][2], as[2 * p][3]); pw.z = cvtpk_s(as[2 * p + 1][0], as[2 * p + 1][1]); pw.w = cvtpk_s(as[2 * p + 1][2], as[2 * p + 1][3]);
; #pragma unroll
;         for (int vh = 0; vh < 2; ++vh) { const u32x4 vw = {va[vh][p].x, va[vh][p].y, vb2[vh][p].x, vb2[vh][p].y};
;             o[vh] = MFMA16(__builtin_bit_cast(bf16x8, pw), __builtin_bit_cast(bf16x8, vw), o[vh]); }
;     }
;     if ((VAR & 1) == 0 || o[0][0] == 12345.678f) {
; #pragma unroll
;     for (int vh = 0; vh < 2; ++vh)
; #pragma unroll
;         for (int j = 0; j < 4; ++j) *(bf16r*)(ob + (size_t)j * DM * 2 + vh * 32 + ol) = (bf16r)(cvtpk_s(o[vh][j], 0.f) & 0xffffu);
;     }
;     ...
;             hgV<1>(lds, vB, mt); vB = *(const u32x4*)(vp + (size_t)(c + 3 < NC ? c + 3 : NC - 1) * 64 * DM);
;             HBAR();
;             if ((VAR & 4) == 0) hgM<1, VAR>(lds, st, ti, lane, ob + (size_t)(c + 1) * 64 * DM * 2, ol);
	ds_write_b16 v136, v0
	ds_write_b16_d16_hi v136, v0 offset:144
	ds_write_b16 v136, v1 offset:288
	ds_write_b16_d16_hi v136, v1 offset:432
	ds_write_b16 v136, v2 offset:576
	v_cndmask_b32_e64 v0, v71, 0, s[14:15]
	v_cndmask_b32_e64 v1, v70, 0, s[46:47]
	v_cndmask_b32_e64 v49, v68, 0, s[42:43]
	v_cndmask_b32_e64 v50, v67, 0, s[40:41]
	v_cndmask_b32_e64 v51, v66, 0, s[38:39]
	v_cndmask_b32_e64 v65, v65, 0, s[36:37]
	v_cndmask_b32_e64 v64, v64, 0, s[34:35]
	v_mfma_f32_16x16x32_bf16 v[24:27], v[40:43], v[32:35], v[24:27]
	v_cvt_pk_bf16_f32 v40, v64, v65
	v_cvt_pk_bf16_f32 v41, v51, v50
	v_cvt_pk_bf16_f32 v42, v49, v48
	v_cvt_pk_bf16_f32 v43, v1, v0
	v_mfma_f32_16x16x32_bf16 v[32:35], v[44:47], v[32:35], v[52:55]
	ds_write_b16_d16_hi v136, v2 offset:720
	ds_write_b16 v136, v3 offset:864
	ds_write_b16_d16_hi v136, v3 offset:1008
	v_mfma_f32_16x16x32_bf16 v[24:27], v[28:31], v[40:43], v[24:27]
	v_mfma_f32_16x16x32_bf16 v[0:3], v[36:39], v[40:43], v[32:35]
	s_nop 6
	v_cvt_pk_bf16_f32 v24, v24, v25
	v_cvt_pk_bf16_f32 v25, v26, v27
	v_cvt_pk_bf16_f32 v26, v0, v1
	v_cvt_pk_bf16_f32 v27, v2, v3
	global_store_dwordx2 v[244:245], v[24:25], off
	global_store_dwordx2 v[244:245], v[26:27], off offset:32
	global_load_dwordx4 v[0:3], v[150:151], off
	v_add_u32_e32 v25, v122, v119
	v_add_u32_e32 v24, v121, v84
	v_add_u32_e32 v26, 0x800, v25
	s_waitcnt lgkmcnt(0)
	s_barrier
	s_sleep 13
	v_add_u32_e32 v112, v122, v84
	v_add_u32_e32 v113, 0x1c600, v95
	ds_read_b128 v[100:103], v99 offset:58368
	ds_read_b128 v[104:107], v99 offset:58432
	ds_read_b128 v[108:111], v24
	ds_read_b128 v[138:141], v24 offset:64
	ds_read_b128 v[142:145], v24 offset:4352
	ds_read_b128 v[146:149], v24 offset:4416
	ds_read_b128 v[68:71], v99 offset:58496
	ds_read_b128 v[36:39], v99 offset:58560
	ds_read_b128 v[72:75], v24 offset:128
	ds_read_b128 v[44:47], v24 offset:192
	ds_read_b128 v[150:153], v24 offset:4480
	ds_read_b128 v[48:51], v24 offset:4544
	ds_read_b128 v[154:157], v137
	ds_read_b128 v[158:161], v137 offset:64
	ds_read_b128 v[162:165], v137 offset:128
	ds_read_b128 v[52:55], v137 offset:192
	ds_read_b128 v[166:169], v137 offset:4352
	ds_read_b128 v[170:173], v137 offset:4416
	ds_read_b128 v[174:177], v137 offset:4480
	ds_read_b128 v[56:59], v137 offset:4544
	ds_read_b128 v[178:181], v137 offset:8704
	ds_read_b128 v[182:185], v137 offset:8768
	ds_read_b128 v[186:189], v137 offset:8832
	ds_read_b128 v[60:63], v137 offset:8896
	ds_read_b128 v[190:193], v137 offset:13056
	ds_read_b128 v[194:197], v137 offset:13120
	ds_read_b128 v[76:79], v137 offset:13184
	ds_read_b128 v[64:67], v137 offset:13248
	ds_read2_b64 v[40:43], v25 offset1:4
	ds_read2_b64 v[28:31], v25 offset0:8 offset1:12
	ds_read2_b64 v[32:35], v26 offset0:32 offset1:36
	ds_read2_b64 v[24:27], v26 offset0:40 offset1:44
	ds_read_b128 v[202:205], v112
	ds_read_b128 v[208:211], v112 offset:64
	ds_read_b128 v[212:215], v112 offset:2304
	ds_read_b128 v[216:219], v112 offset:2368
	ds_read_b128 v[220:223], v97
	ds_read_b128 v[224:227], v97 offset:64
	ds_read_b128 v[228:231], v97 offset:2304
	ds_read_b128 v[232:235], v97 offset:2368
	ds_read_b128 v[236:239], v113
	ds_read_b128 v[240:243], v113 offset:64
	s_waitcnt lgkmcnt(14)
	v_mfma_f32_16x16x32_bf16 v[142:145], v[142:145], v[100:103], 0
	s_waitcnt lgkmcnt(1)
	v_pk_mul_f32 v[22:23], v[22:23], v[238:239]
	v_pk_mul_f32 v[20:21], v[20:21], v[236:237]
	v_pk_mul_f32 v[18:19], v[18:19], v[238:239]
	v_mfma_f32_16x16x32_bf16 v[154:157], v[154:157], v[100:103], 0
	v_mul_f32_e64 v16, v16, v236
	v_mul_f32_e64 v17, v17, v237
	s_waitcnt lgkmcnt(0)
; __device__ __forceinline__ unsigned cvtpk_s(float lo, float hi) { f32x2_t v = {lo, hi}; bf16x2_t b = __builtin_convertvector(v, bf16x2_t); return __builtin_bit_cast(unsigned, b); }
; #define HBAR() do { asm volatile("s_waitcnt lgkmcnt(0)" ::: "memory"); __builtin_amdgcn_s_barrier(); asm volatile("" ::: "memory"); } while (0)
; #define MFMA16(a, b, c) __builtin_amdgcn_mfma_f32_16x16x32_bf16((a), (b), (c), 0, 0, 0)
;     ...
;     for (int kk = 0; kk < 4; ++kk) { o[0] = MFMA16(qf[kk], sb[0][kk], o[0]); o[1] = MFMA16(qf[kk], sb[1][kk], o[1]);
; #pragma unroll
;         for (int si = 0; si < 4; ++si) as[si] = MFMA16(kf[si][kk], qf[kk], as[si]); }
; #pragma unroll
;     for (int ds = 0; ds < 2; ++ds)
; #pragma unroll
;         for (int vh = 0; vh < 2; ++vh) { st[ds][vh] = st[ds][vh] * dl[ds];
; #pragma unroll
;             for (int kk = 0; kk < 2; ++kk) st[ds][vh] = MFMA16(kt[ds][kk], vv[vh][kk], st[ds][vh]); }
;     const int tq = 16 * ti + l16 - 4 * kq;
; #pragma unroll
;     for (int si = 0; si < 4; ++si)
; #pragma unroll
;         for (int j = 0; j < 4; ++j) if (16 * si + j > tq) as[si][j] = 0.f;
; #pragma unroll
;     for (int p = 0; p < 2; ++p) {
;         u32x4 pw; pw.x = cvtpk_s(as[2 * p][0], as[2 * p][1]); pw.y = cvtpk_s(as[2 * p][2], as[2 * p][3]); pw.z = cvtpk_s(as[2 * p + 1][0], as[2 * p + 1][1]); pw.w = cvtpk_s(as[2 * p + 1][2], as[2 * p + 1][3]);
; #pragma unroll
;         for (int vh = 0; vh < 2; ++vh) { const u32x4 vw = {va[vh][p].x, va[vh][p].y, vb2[vh][p].x, vb2[vh][p].y};
;             o[vh] = MFMA16(__builtin_bit_cast(bf16x8, pw), __builtin_bit_cast(bf16x8, vw), o[vh]); }
;     }
;     if ((VAR & 1) == 0 || o[0][0] == 12345.678f) {
; #pragma unroll
;     for (int vh = 0; vh < 2; ++vh)
; #pragma unroll
;         for (int j = 0; j < 4; ++j) *(bf16r*)(ob + (size_t)j * DM * 2 + vh * 32 + ol) = (bf16r)(cvtpk_s(o[vh][j], 0.f) & 0xffffu);
;     }
;     ...
;             if ((VAR & 4) == 0) hgM<1, VAR>(lds, st, ti, lane, ob + (size_t)(c + 1) * 64 * DM * 2, ol);
;             hgV<0>(lds, vA, mt); vA = *(const u32x4*)(vp + (size_t)(c + 4 < NC ? c + 4 : NC - 1) * 64 * DM);
;             HBAR();
	v_pk_mul_f32 v[14:15], v[14:15], v[242:243]
	v_pk_mul_f32 v[12:13], v[12:13], v[240:241]
	v_mfma_f32_16x16x32_bf16 v[166:169], v[166:169], v[100:103], 0
	v_mul_f32_e64 v10, v10, v242
	v_mul_f32_e64 v11, v11, v243
	v_pk_mul_f32 v[8:9], v[8:9], v[240:241]
	s_mov_b32 s0, 0x40000
	v_mfma_f32_16x16x32_bf16 v[178:181], v[178:181], v[100:103], 0
	v_add_co_u32_e32 v112, vcc, s0, v92
	s_mov_b32 s0, 0x42000
	v_mfma_f32_16x16x32_bf16 v[190:193], v[190:193], v[100:103], 0
	v_addc_co_u32_e32 v113, vcc, 0, v93, vcc
	v_mfma_f32_16x16x32_bf16 v[100:103], v[108:111], v[100:103], 0
	v_mfma_f32_16x16x32_bf16 v[20:23], v[220:223], v[202:205], v[20:23]
	v_mfma_f32_16x16x32_bf16 v[16:19], v[220:223], v[212:215], v[16:19]
	v_mfma_f32_16x16x32_bf16 v[12:15], v[228:231], v[202:205], v[12:15]
	v_mfma_f32_16x16x32_bf16 v[108:111], v[228:231], v[212:215], v[8:11]
	v_mfma_f32_16x16x32_bf16 v[142:145], v[146:149], v[104:107], v[142:145]
	v_mfma_f32_16x16x32_bf16 v[146:149], v[158:161], v[104:107], v[154:157]
	v_mfma_f32_16x16x32_bf16 v[154:157], v[170:173], v[104:107], v[166:169]
	v_mfma_f32_16x16x32_bf16 v[158:161], v[182:185], v[104:107], v[178:181]
	v_mfma_f32_16x16x32_bf16 v[166:169], v[194:197], v[104:107], v[190:193]
	v_mfma_f32_16x16x32_bf16 v[100:103], v[138:141], v[104:107], v[100:103]
	v_mfma_f32_16x16x32_bf16 v[8:11], v[224:227], v[208:211], v[20:23]
	v_mfma_f32_16x16x32_bf16 v[20:23], v[224:227], v[216:219], v[16:19]
	v_mfma_f32_16x16x32_bf16 v[16:19], v[232:235], v[208:211], v[12:15]
	v_mfma_f32_16x16x32_bf16 v[12:15], v[232:235], v[216:219], v[108:111]
	v_mfma_f32_16x16x32_bf16 v[108:111], v[162:165], v[68:71], v[146:149]
	v_mfma_f32_16x16x32_bf16 v[138:141], v[174:177], v[68:71], v[154:157]
	v_mfma_f32_16x16x32_bf16 v[104:107], v[150:153], v[68:71], v[142:145]
	s_nop 1
	v_add_u32_e32 v154, v117, v94
	v_add_co_u32_e32 v150, vcc, s70, v92
	v_mfma_f32_16x16x32_bf16 v[142:145], v[186:189], v[68:71], v[158:161]
	s_nop 0
	v_addc_co_u32_e32 v151, vcc, 0, v93, vcc
	v_add_co_u32_e32 v146, vcc, s0, v92
	v_mfma_f32_16x16x32_bf16 v[76:79], v[76:79], v[68:71], v[166:169]
	s_nop 0
	v_addc_co_u32_e32 v147, vcc, 0, v93, vcc
	s_min_u32 s0, s3, 0x7b
	v_mfma_f32_16x16x32_bf16 v[68:71], v[72:75], v[68:71], v[100:103]
	v_cvt_pk_bf16_f32 v72, v8, v9
	v_cvt_pk_bf16_f32 v73, v10, v11
	v_cvt_pk_bf16_f32 v74, v20, v21
	v_mfma_f32_16x16x32_bf16 v[52:55], v[52:55], v[36:39], v[108:111]
	v_cvt_pk_bf16_f32 v102, v12, v13
	v_cvt_pk_bf16_f32 v103, v14, v15
	v_cvt_pk_bf16_f32 v75, v22, v23
	v_mfma_f32_16x16x32_bf16 v[56:59], v[56:59], v[36:39], v[138:141]
	v_cvt_pk_bf16_f32 v100, v16, v17
	s_nop 2
	v_cndmask_b32_e64 v54, v54, 0, s[20:21]
	v_cndmask_b32_e64 v52, v52, 0, s[64:65]
	v_mfma_f32_16x16x32_bf16 v[48:51], v[48:51], v[36:39], v[104:107]
	v_cvt_pk_bf16_f32 v101, v18, v19
	v_cndmask_b32_e64 v58, v58, 0, s[28:29]
	v_cndmask_b32_e64 v56, v56, 0, s[24:25]
	v_mfma_f32_16x16x32_bf16 v[60:63], v[60:63], v[36:39], v[142:145]
	ds_write_b64 v154, v[72:73]
	ds_write_b64 v154, v[74:75] offset:4352
	ds_write_b64 v98, v[100:101]
	ds_write_b64 v98, v[102:103] offset:4352
	s_waitcnt vmcnt(3)
	ds_write_b16 v135, v4 offset:53248
	ds_write_b16_d16_hi v135, v4 offset:53392
	ds_write_b16 v135, v5 offset:53536
	ds_write_b16_d16_hi v135, v5 offset:53680
	ds_write_b16 v135, v6 offset:53824
	v_mfma_f32_16x16x32_bf16 v[64:67], v[64:67], v[36:39], v[76:79]
	v_cndmask_b32_e64 v63, v63, 0, s[40:41]
	v_cndmask_b32_e64 v62, v62, 0, s[38:39]
	v_cndmask_b32_e64 v61, v61, 0, s[36:37]
	v_mfma_f32_16x16x32_bf16 v[36:39], v[44:47], v[36:39], v[68:71]
	v_cndmask_b32_e64 v47, v59, 0, s[30:31]
	v_cndmask_b32_e64 v46, v57, 0, s[26:27]
	v_cndmask_b32_e64 v45, v55, 0, s[22:23]
	v_cndmask_b32_e64 v44, v53, 0, s[16:17]
	v_cvt_pk_bf16_f32 v44, v52, v44
	v_cvt_pk_bf16_f32 v45, v54, v45
	v_cvt_pk_bf16_f32 v46, v56, v46
	v_cvt_pk_bf16_f32 v47, v58, v47
	v_cndmask_b32_e64 v4, v67, 0, s[14:15]
	v_cndmask_b32_e64 v5, v66, 0, s[46:47]
	v_cndmask_b32_e64 v65, v65, 0, s[44:45]
	v_cndmask_b32_e64 v64, v64, 0, s[42:43]
	v_cndmask_b32_e64 v60, v60, 0, s[34:35]
	v_mfma_f32_16x16x32_bf16 v[36:39], v[40:43], v[44:47], v[36:39]
	v_cvt_pk_bf16_f32 v40, v60, v61
	v_cvt_pk_bf16_f32 v41, v62, v63
	v_cvt_pk_bf16_f32 v42, v64, v65
	v_cvt_pk_bf16_f32 v43, v5, v4
	v_mfma_f32_16x16x32_bf16 v[32:35], v[32:35], v[44:47], v[48:51]
	ds_write_b16_d16_hi v135, v6 offset:53968
	ds_write_b16 v135, v7 offset:54112
	ds_write_b16_d16_hi v135, v7 offset:54256
	v_add_co_u32_e32 v148, vcc, s71, v92
	v_mfma_f32_16x16x32_bf16 v[28:31], v[28:31], v[40:43], v[36:39]
	s_lshl_b32 s48, s0, 18
	v_addc_co_u32_e32 v149, vcc, 0, v93, vcc
	v_mfma_f32_16x16x32_bf16 v[4:7], v[24:27], v[40:43], v[32:35]
	v_lshl_add_u64 v[152:153], v[90:91], 0, s[48:49]
	v_add_co_u32_e32 v152, vcc, 0x100000, v152
	s_nop 2
	v_cvt_pk_bf16_f32 v24, v28, v29
	v_addc_co_u32_e32 v153, vcc, 0, v153, vcc
	v_cvt_pk_bf16_f32 v25, v30, v31
	v_cvt_pk_bf16_f32 v26, v4, v5
	v_cvt_pk_bf16_f32 v27, v6, v7
	global_store_dwordx2 v[246:247], v[24:25], off
	global_store_dwordx2 v[246:247], v[26:27], off offset:32
	global_load_dwordx4 v[4:7], v[152:153], off
	s_waitcnt lgkmcnt(0)
	s_barrier
	s_sleep 13
	s_mov_b64 s[0:1], 0x80000
	s_cmpk_lt_u32 s3, 0x7e
	v_lshl_add_u64 v[92:93], v[92:93], 0, s[0:1]
	v_lshl_add_u64 v[244:245], v[244:245], 0, s[0:1]
	v_lshl_add_u64 v[246:247], v[246:247], 0, s[0:1]
	s_cbranch_scc1 .LBB0_1179
	s_mov_b64 s[16:17], 0

; __device__ __forceinline__ unsigned cvtpk_s(float lo, float hi) { f32x2_t v = {lo, hi}; bf16x2_t b = __builtin_convertvector(v, bf16x2_t); return __builtin_bit_cast(unsigned, b); }
; __device__ __forceinline__ float bf_lo(unsigned w) { return __uint_as_float(w << 16); }
; __device__ __forceinline__ float bf_hi(unsigned w) { return __uint_as_float(w & 0xffff0000u); }
; #define LAS __attribute__((address_space(3)))
; template <int SET> __device__ __forceinline__ void hgE(LAS unsigned char* lds, const unsigned (&gh)[16], const unsigned (&qv)[16], int w, int lane) {
;     ...
;     f32x2 gv[16];
; #pragma unroll
;     for (int j = 0; j < 16; ++j) { const f16x2_t t = __builtin_bit_cast(f16x2_t, gh[j]); gv[j] = (f32x2){(float)t.x, (float)t.y}; }
;     const int cp = lane & 15, rg = lane >> 4;
;     float run0 = 1.f, run1 = 1.f;
; #pragma unroll
;     for (int j = 0; j < 16; ++j) { run0 *= gv[j].x; run1 *= gv[j].y; }
;     float i0 = run0, i1 = run1;
;     { const float a0 = __shfl_up(i0, 16), a1 = __shfl_up(i1, 16); if (rg >= 1) { i0 *= a0; i1 *= a1; } }
;     { const float a0 = __shfl_up(i0, 32), a1 = __shfl_up(i1, 32); if (rg >= 2) { i0 *= a0; i1 *= a1; } }
;     float pre0 = __shfl_up(i0, 16), pre1 = __shfl_up(i1, 16); if (rg == 0) { pre0 = 1.f; pre1 = 1.f; }
;     const float all0 = __shfl(i0, cp + 48), all1 = __shfl(i1, cp + 48);
;     unsigned kh0[8], kh1[8]; float kp0 = 0.f, kp1 = 0.f, ea = pre0, eb = pre1;
;     LAS unsigned char* qw = base + OFF_Q + (16 * rg) * QS + (32 * w + 2 * cp) * 2;
; #pragma unroll
;     for (int j = 0; j < 16; ++j) {
;         ea *= gv[j].x; eb *= gv[j].y;
;         const float qa = bf_lo(qv[j]) * ea, qb = bf_hi(qv[j]) * eb;
;         const float ka = (1.f - gv[j].x) * __builtin_amdgcn_rcpf(ea), kb = (1.f - gv[j].y) * __builtin_amdgcn_rcpf(eb);
;         *(LAS unsigned*)(qw + j * QS) = cvtpk_s(qa, qb);
;         *(LAS unsigned*)(qw + (OFF_K - OFF_Q) + j * QS) = cvtpk_s(ka, kb);
;         const float ha = ka * all0, hb = kb * all1;
;         if (j & 1) { kh0[j >> 1] = cvtpk_s(kp0, ha); kh1[j >> 1] = cvtpk_s(kp1, hb); } else { kp0 = ha; kp1 = hb; }
;     }
.LBB0_1188:
	s_waitcnt vmcnt(62)
	v_cvt_f32_f16_sdwa v21, v151 dst_sel:DWORD dst_unused:UNUSED_PAD src0_sel:WORD_1
	v_cvt_f32_f16_e32 v20, v151
	s_waitcnt vmcnt(56)
	v_cvt_f32_f16_sdwa v23, v154 dst_sel:DWORD dst_unused:UNUSED_PAD src0_sel:WORD_1
	v_cvt_f32_f16_e32 v22, v154
	v_cvt_f32_f16_sdwa v105, v148 dst_sel:DWORD dst_unused:UNUSED_PAD src0_sel:WORD_1
	v_cvt_f32_f16_e32 v104, v148
	v_cvt_f32_f16_sdwa v111, v147 dst_sel:DWORD dst_unused:UNUSED_PAD src0_sel:WORD_1
	v_cvt_f32_f16_e32 v110, v147
	v_lshlrev_b32_e32 v108, 16, v149
	v_and_b32_e32 v109, 0xffff0000, v149
	v_lshlrev_b32_e32 v148, 16, v146
	v_and_b32_e32 v149, 0xffff0000, v146
	s_waitcnt vmcnt(55)
	v_cvt_f32_f16_sdwa v147, v164 dst_sel:DWORD dst_unused:UNUSED_PAD src0_sel:WORD_1
	v_cvt_f32_f16_e32 v146, v164
	v_pk_mul_f32 v[18:19], v[22:23], v[20:21]
	s_waitcnt vmcnt(54)
	v_lshlrev_b32_e32 v192, 16, v163
	v_and_b32_e32 v193, 0xffff0000, v163
	s_waitcnt vmcnt(48)
	v_cvt_f32_f16_sdwa v163, v162 dst_sel:DWORD dst_unused:UNUSED_PAD src0_sel:WORD_1
	v_cvt_f32_f16_e32 v162, v162
	v_pk_mul_f32 v[18:19], v[18:19], v[104:105]
	v_cvt_f32_f16_sdwa v93, v155 dst_sel:DWORD dst_unused:UNUSED_PAD src0_sel:WORD_1
	v_pk_mul_f32 v[18:19], v[18:19], v[110:111]
	v_cvt_f32_f16_e32 v92, v155
	v_pk_mul_f32 v[18:19], v[18:19], v[146:147]
	s_waitcnt vmcnt(47)
	v_cvt_f32_f16_sdwa v69, v175 dst_sel:DWORD dst_unused:UNUSED_PAD src0_sel:WORD_1
	v_pk_mul_f32 v[28:29], v[18:19], v[162:163]
	v_cvt_f32_f16_sdwa v19, v158 dst_sel:DWORD dst_unused:UNUSED_PAD src0_sel:WORD_1
	v_cvt_f32_f16_e32 v18, v158
	v_cvt_f32_f16_e32 v68, v175
	s_waitcnt vmcnt(40)
	v_cvt_f32_f16_sdwa v67, v173 dst_sel:DWORD dst_unused:UNUSED_PAD src0_sel:WORD_1
	v_cvt_f32_f16_e32 v66, v173
	v_pk_mul_f32 v[28:29], v[28:29], v[18:19]
	v_cvt_f32_f16_sdwa v53, v168 dst_sel:DWORD dst_unused:UNUSED_PAD src0_sel:WORD_1
	v_cvt_f32_f16_e32 v52, v168
	v_pk_mul_f32 v[28:29], v[28:29], v[92:93]
	v_cvt_f32_f16_sdwa v51, v166 dst_sel:DWORD dst_unused:UNUSED_PAD src0_sel:WORD_1
	v_cvt_f32_f16_e32 v50, v166
	v_pk_mul_f32 v[28:29], v[28:29], v[68:69]
	s_waitcnt vmcnt(39)
	v_cvt_f32_f16_sdwa v41, v178 dst_sel:DWORD dst_unused:UNUSED_PAD src0_sel:WORD_1
	v_cvt_f32_f16_e32 v40, v178
	v_pk_mul_f32 v[28:29], v[28:29], v[66:67]
	s_waitcnt vmcnt(32)
	v_cvt_f32_f16_sdwa v39, v179 dst_sel:DWORD dst_unused:UNUSED_PAD src0_sel:WORD_1
	v_cvt_f32_f16_e32 v38, v179
	v_pk_mul_f32 v[28:29], v[28:29], v[52:53]
	v_cvt_f32_f16_sdwa v35, v177 dst_sel:DWORD dst_unused:UNUSED_PAD src0_sel:WORD_1
	v_cvt_f32_f16_e32 v34, v177
	v_pk_mul_f32 v[28:29], v[28:29], v[50:51]
	v_cvt_f32_f16_sdwa v33, v176 dst_sel:DWORD dst_unused:UNUSED_PAD src0_sel:WORD_1
	v_cvt_f32_f16_e32 v32, v176
	v_pk_mul_f32 v[28:29], v[28:29], v[40:41]
	v_lshlrev_b32_e32 v16, 16, v153
	v_pk_mul_f32 v[28:29], v[28:29], v[38:39]
	v_and_b32_e32 v17, 0xffff0000, v153
	v_pk_mul_f32 v[28:29], v[28:29], v[34:35]
	v_pk_add_f32 v[100:101], v[20:21], 1.0 op_sel_hi:[1,0] neg_lo:[1,0] neg_hi:[1,0]
	v_pk_mul_f32 v[28:29], v[28:29], v[32:33]
	v_mov_b32_e32 v216, v28
	v_mov_b32_e32 v217, v29
	v_mov_b32_e32 v218, v28
	v_mov_b32_e32 v219, v29
	s_nop 1
	v_permlane16_swap_b32_e32 v216, v218
	v_permlane16_swap_b32_e32 v217, v219
	v_pk_mul_f32 v[220:221], v[216:217], v[218:219]
	v_mov_b32_e32 v228, 1.0
	v_mov_b32_e32 v229, 1.0
	v_mov_b32_e32 v222, v220
	v_mov_b32_e32 v223, v221
	s_nop 1
	v_permlane32_swap_b32_e32 v222, v220
	v_permlane32_swap_b32_e32 v223, v221
	v_permlane16_swap_b32_e32 v228, v216
	v_permlane16_swap_b32_e32 v229, v217
	v_pk_mul_f32 v[224:225], v[222:223], v[220:221]
	v_cndmask_b32_e64 v226, 1.0, v222, s[10:11]
	v_cndmask_b32_e64 v227, 1.0, v223, s[10:11]
	v_pk_mul_f32 v[28:29], v[226:227], v[228:229]
	v_lshlrev_b32_e32 v196, 16, v161
	v_and_b32_e32 v197, 0xffff0000, v161
	v_lshlrev_b32_e32 v78, 16, v160
	v_and_b32_e32 v79, 0xffff0000, v160
	v_pk_add_f32 v[106:107], v[22:23], 1.0 op_sel_hi:[1,0] neg_lo:[1,0] neg_hi:[1,0]
	v_lshlrev_b32_e32 v102, 16, v150
	v_and_b32_e32 v103, 0xffff0000, v150
	v_pk_add_f32 v[112:113], v[104:105], 1.0 op_sel_hi:[1,0] neg_lo:[1,0] neg_hi:[1,0]
	v_pk_add_f32 v[150:151], v[110:111], 1.0 op_sel_hi:[1,0] neg_lo:[1,0] neg_hi:[1,0]
	v_pk_mul_f32 v[20:21], v[28:29], v[20:21]
	v_mov_b32_e32 v28, v224
	v_rcp_f32_e32 v160, v20
	v_rcp_f32_e32 v161, v21
	v_pk_mul_f32 v[16:17], v[20:21], v[16:17]
	v_pk_mul_f32 v[20:21], v[20:21], v[22:23]
	v_cvt_pk_bf16_f32 v29, v16, v17
	v_rcp_f32_e32 v22, v20
	v_rcp_f32_e32 v23, v21
	v_pk_mul_f32 v[16:17], v[20:21], v[102:103]
	v_pk_mul_f32 v[100:101], v[100:101], v[160:161]
	v_cvt_pk_bf16_f32 v16, v16, v17
	v_pk_mul_f32 v[22:23], v[106:107], v[22:23]
	v_mov_b32_e32 v30, v225
	v_cvt_pk_bf16_f32 v31, v100, v101
	ds_write2_b32 v159, v29, v16 offset1:68
	v_cvt_pk_bf16_f32 v16, v22, v23
	v_add_u32_e32 v29, 0x4400, v159
	ds_write2_b32 v29, v31, v16 offset1:68
	v_mov_b32_e32 v16, v101
	v_mov_b32_e32 v101, v22
	v_mov_b32_e32 v17, v23
	s_waitcnt lgkmcnt(3)
	v_pk_mul_f32 v[22:23], v[100:101], v[28:29] op_sel_hi:[1,0]
	v_pk_mul_f32 v[100:101], v[20:21], v[104:105]
	v_cvt_pk_bf16_f32 v20, v22, v23
	v_rcp_f32_e32 v102, v100
	v_rcp_f32_e32 v103, v101
	v_pk_mul_f32 v[22:23], v[100:101], v[108:109]
	v_pk_mul_f32 v[100:101], v[100:101], v[110:111]
	s_waitcnt lgkmcnt(2)
; __device__ __forceinline__ unsigned cvtpk_s(float lo, float hi) { f32x2_t v = {lo, hi}; bf16x2_t b = __builtin_convertvector(v, bf16x2_t); return __builtin_bit_cast(unsigned, b); }
; __device__ __forceinline__ float bf_lo(unsigned w) { return __uint_as_float(w << 16); }
; __device__ __forceinline__ float bf_hi(unsigned w) { return __uint_as_float(w & 0xffff0000u); }
; #define LAS __attribute__((address_space(3)))
; template <int SET> __device__ __forceinline__ void hgE(LAS unsigned char* lds, const unsigned (&gh)[16], const unsigned (&qv)[16], int w, int lane) {
;     ...
; #pragma unroll
;     for (int j = 0; j < 16; ++j) {
;         ea *= gv[j].x; eb *= gv[j].y;
;         const float qa = bf_lo(qv[j]) * ea, qb = bf_hi(qv[j]) * eb;
;         const float ka = (1.f - gv[j].x) * __builtin_amdgcn_rcpf(ea), kb = (1.f - gv[j].y) * __builtin_amdgcn_rcpf(eb);
;         *(LAS unsigned*)(qw + j * QS) = cvtpk_s(qa, qb);
;         *(LAS unsigned*)(qw + (OFF_K - OFF_Q) + j * QS) = cvtpk_s(ka, kb);
;         const float ha = ka * all0, hb = kb * all1;
;         if (j & 1) { kh0[j >> 1] = cvtpk_s(kp0, ha); kh1[j >> 1] = cvtpk_s(kp1, hb); } else { kp0 = ha; kp1 = hb; }
;     }
;     LAS unsigned char* kw = base + OFF_KT + (32 * w + 2 * cp) * TS + rg * 32;
;     *(LAS u32x4*)(kw) = (u32x4){kh0[0], kh0[1], kh0[2], kh0[3]}; *(LAS u32x4*)(kw + 16) = (u32x4){kh0[4], kh0[5], kh0[6], kh0[7]};
;     *(LAS u32x4*)(kw + TS) = (u32x4){kh1[0], kh1[1], kh1[2], kh1[3]}; *(LAS u32x4*)(kw + TS + 16) = (u32x4){kh1[4], kh1[5], kh1[6], kh1[7]};
;     if (rg == 0) *(LAS f32x2*)(base + OFF_DL + (32 * w + 2 * cp) * 4) = (f32x2){all0, all1};
	v_pk_mul_f32 v[16:17], v[16:17], v[30:31] op_sel_hi:[1,0]
	v_rcp_f32_e32 v104, v100
	v_rcp_f32_e32 v105, v101
	v_cvt_pk_bf16_f32 v16, v16, v17
	v_cvt_pk_bf16_f32 v17, v22, v23
	v_pk_mul_f32 v[22:23], v[100:101], v[148:149]
	v_pk_mul_f32 v[102:103], v[112:113], v[102:103]
	v_pk_mul_f32 v[104:105], v[150:151], v[104:105]
	v_cvt_pk_bf16_f32 v22, v22, v23
	v_pk_mul_f32 v[100:101], v[100:101], v[146:147]
	v_cvt_pk_bf16_f32 v21, v102, v103
	ds_write2_b32 v159, v17, v22 offset0:136 offset1:204
	v_cvt_pk_bf16_f32 v17, v104, v105
	v_mov_b32_e32 v22, v103
	v_mov_b32_e32 v23, v105
	v_mov_b32_e32 v103, v104
	v_rcp_f32_e32 v104, v100
	v_rcp_f32_e32 v105, v101
	v_pk_mul_f32 v[22:23], v[22:23], v[30:31] op_sel_hi:[1,0]
	v_pk_add_f32 v[194:195], v[146:147], 1.0 op_sel_hi:[1,0] neg_lo:[1,0] neg_hi:[1,0]
	ds_write2_b32 v29, v21, v17 offset0:136 offset1:204
	v_pk_mul_f32 v[102:103], v[102:103], v[28:29] op_sel_hi:[1,0]
	v_cvt_pk_bf16_f32 v17, v22, v23
	v_pk_mul_f32 v[22:23], v[100:101], v[192:193]
	v_pk_mul_f32 v[100:101], v[100:101], v[162:163]
	v_cvt_pk_bf16_f32 v21, v102, v103
	v_pk_mul_f32 v[102:103], v[194:195], v[104:105]
	v_rcp_f32_e32 v104, v100
	v_rcp_f32_e32 v105, v101
	v_pk_add_f32 v[198:199], v[162:163], 1.0 op_sel_hi:[1,0] neg_lo:[1,0] neg_hi:[1,0]
	v_cvt_pk_bf16_f32 v29, v22, v23
	v_pk_mul_f32 v[22:23], v[100:101], v[196:197]
	v_pk_mul_f32 v[104:105], v[198:199], v[104:105]
	v_cvt_pk_bf16_f32 v22, v22, v23
	v_add_u32_e32 v98, 0xe800, v89
	v_cvt_pk_bf16_f32 v31, v102, v103
	ds_write2_b32 v98, v29, v22 offset0:16 offset1:84
	v_cvt_pk_bf16_f32 v22, v104, v105
	v_add_u32_e32 v29, 0x4800, v159
	v_pk_mul_f32 v[100:101], v[100:101], v[18:19]
	v_lshlrev_b32_e32 v76, 16, v152
	v_and_b32_e32 v77, 0xffff0000, v152
	v_pk_add_f32 v[152:153], v[92:93], 1.0 op_sel_hi:[1,0] neg_lo:[1,0] neg_hi:[1,0]
	ds_write2_b32 v29, v31, v22 offset0:16 offset1:84
	v_mov_b32_e32 v22, v103
	v_mov_b32_e32 v23, v105
	v_mov_b32_e32 v103, v104
	v_pk_mul_f32 v[92:93], v[100:101], v[92:93]
	v_pk_add_f32 v[72:73], v[68:69], 1.0 op_sel_hi:[1,0] neg_lo:[1,0] neg_hi:[1,0]
	v_pk_mul_f32 v[106:107], v[22:23], v[30:31] op_sel_hi:[1,0]
	v_pk_mul_f32 v[22:23], v[102:103], v[28:29] op_sel_hi:[1,0]
	v_rcp_f32_e32 v102, v100
	v_rcp_f32_e32 v103, v101
	v_pk_mul_f32 v[78:79], v[100:101], v[78:79]
	v_rcp_f32_e32 v100, v92
	v_rcp_f32_e32 v101, v93
	v_pk_mul_f32 v[68:69], v[92:93], v[68:69]
	v_lshlrev_b32_e32 v62, 16, v174
	v_and_b32_e32 v63, 0xffff0000, v174
	v_pk_add_f32 v[74:75], v[66:67], 1.0 op_sel_hi:[1,0] neg_lo:[1,0] neg_hi:[1,0]
	v_pk_mul_f32 v[66:67], v[68:69], v[66:67]
	v_pk_mul_f32 v[76:77], v[92:93], v[76:77]
	v_rcp_f32_e32 v92, v68
	v_rcp_f32_e32 v93, v69
	v_pk_mul_f32 v[62:63], v[68:69], v[62:63]
	v_rcp_f32_e32 v68, v66
	v_rcp_f32_e32 v69, v67
	v_pk_add_f32 v[154:155], v[18:19], 1.0 op_sel_hi:[1,0] neg_lo:[1,0] neg_hi:[1,0]
	v_lshlrev_b32_e32 v60, 16, v172
	v_and_b32_e32 v61, 0xffff0000, v172
	v_pk_mul_f32 v[102:103], v[154:155], v[102:103]
	v_cvt_pk_bf16_f32 v19, v78, v79
	v_pk_mul_f32 v[78:79], v[152:153], v[100:101]
	v_cvt_pk_bf16_f32 v31, v76, v77
	v_cvt_pk_bf16_f32 v22, v22, v23
	v_cvt_pk_bf16_f32 v23, v102, v103
	ds_write2_b32 v98, v19, v31 offset0:152 offset1:220
	v_cvt_pk_bf16_f32 v19, v78, v79
	v_mov_b32_e32 v76, v103
	v_mov_b32_e32 v103, v78
	v_pk_mul_f32 v[60:61], v[66:67], v[60:61]
	ds_write2_b32 v29, v23, v19 offset0:152 offset1:220
	v_mov_b32_e32 v77, v79
	v_pk_mul_f32 v[78:79], v[102:103], v[28:29] op_sel_hi:[1,0]
	v_pk_mul_f32 v[72:73], v[72:73], v[92:93]
	v_cvt_pk_bf16_f32 v29, v62, v63
	v_pk_mul_f32 v[62:63], v[74:75], v[68:69]
	v_cvt_pk_bf16_f32 v60, v60, v61
	v_add_u32_e32 v74, 0xec00, v89
	v_pk_mul_f32 v[76:77], v[76:77], v[30:31] op_sel_hi:[1,0]
	v_cvt_pk_bf16_f32 v31, v72, v73
	ds_write2_b32 v74, v29, v60 offset0:32 offset1:100
	v_cvt_pk_bf16_f32 v29, v62, v63
	v_mov_b32_e32 v60, v73
	v_mov_b32_e32 v73, v62
	v_pk_mul_f32 v[66:67], v[66:67], v[52:53]
	v_pk_add_f32 v[54:55], v[50:51], 1.0 op_sel_hi:[1,0] neg_lo:[1,0] neg_hi:[1,0]
	v_mov_b32_e32 v61, v63
	v_pk_mul_f32 v[62:63], v[72:73], v[28:29] op_sel_hi:[1,0]
	v_pk_mul_f32 v[50:51], v[66:67], v[50:51]
	v_pk_add_f32 v[58:59], v[52:53], 1.0 op_sel_hi:[1,0] neg_lo:[1,0] neg_hi:[1,0]
	v_rcp_f32_e32 v68, v66
	v_rcp_f32_e32 v69, v67
	v_cvt_pk_bf16_f32 v52, v62, v63
	v_rcp_f32_e32 v62, v50
	v_rcp_f32_e32 v63, v51
	v_pk_add_f32 v[90:91], v[40:41], 1.0 op_sel_hi:[1,0] neg_lo:[1,0] neg_hi:[1,0]
	v_pk_mul_f32 v[40:41], v[50:51], v[40:41]
	v_lshlrev_b32_e32 v48, 16, v169
	v_and_b32_e32 v49, 0xffff0000, v169
	v_lshlrev_b32_e32 v46, 16, v165
	v_and_b32_e32 v47, 0xffff0000, v165
	v_lshlrev_b32_e32 v36, 16, v180
	v_and_b32_e32 v37, 0xffff0000, v180
	v_pk_add_f32 v[70:71], v[38:39], 1.0 op_sel_hi:[1,0] neg_lo:[1,0] neg_hi:[1,0]
	v_pk_mul_f32 v[38:39], v[40:41], v[38:39]
	v_add_u32_e32 v75, 0x4c00, v159
	v_pk_mul_f32 v[48:49], v[66:67], v[48:49]
	v_pk_mul_f32 v[46:47], v[50:51], v[46:47]
	v_rcp_f32_e32 v50, v40
	v_rcp_f32_e32 v51, v41
	v_pk_mul_f32 v[36:37], v[40:41], v[36:37]
	v_rcp_f32_e32 v40, v38
	v_rcp_f32_e32 v41, v39
	ds_write2_b32 v75, v31, v29 offset0:32 offset1:100
	v_pk_mul_f32 v[58:59], v[58:59], v[68:69]
	v_cvt_pk_bf16_f32 v29, v48, v49
	v_pk_mul_f32 v[48:49], v[54:55], v[62:63]
	v_cvt_pk_bf16_f32 v46, v46, v47
	v_lshlrev_b32_e32 v64, 16, v171
	v_and_b32_e32 v65, 0xffff0000, v171
	v_pk_mul_f32 v[60:61], v[60:61], v[30:31] op_sel_hi:[1,0]
	v_cvt_pk_bf16_f32 v31, v58, v59
	ds_write2_b32 v74, v29, v46 offset0:168 offset1:236
	v_cvt_pk_bf16_f32 v29, v48, v49
	v_mov_b32_e32 v46, v59
	v_mov_b32_e32 v47, v49
	v_mov_b32_e32 v59, v48
	ds_write2_b32 v75, v31, v29 offset0:168 offset1:236
	v_pk_mul_f32 v[46:47], v[46:47], v[30:31] op_sel_hi:[1,0]
; #define LAS __attribute__((address_space(3)))
; #define HBAR() do { asm volatile("s_waitcnt lgkmcnt(0)" ::: "memory"); __builtin_amdgcn_s_barrier(); asm volatile("" ::: "memory"); } while (0)
; #define HG_LOADE(GV, QV, c_) do { const size_t adv_ = (size_t)(c_) * 64 * DM; _Pragma("unroll") for (int j = 0; j < 16; ++j) { GV[j] = *(const unsigned*)(gp + adv_ + (size_t)j * DM); QV[j] = *(const unsigned*)(qp + adv_ + (size_t)j * DM); } } while (0)
; template <int SET> __device__ __forceinline__ void hgE(LAS unsigned char* lds, const unsigned (&gh)[16], const unsigned (&qv)[16], int w, int lane) {
;     ...
;     LAS unsigned char* kw = base + OFF_KT + (32 * w + 2 * cp) * TS + rg * 32;
;     *(LAS u32x4*)(kw) = (u32x4){kh0[0], kh0[1], kh0[2], kh0[3]}; *(LAS u32x4*)(kw + 16) = (u32x4){kh0[4], kh0[5], kh0[6], kh0[7]};
;     *(LAS u32x4*)(kw + TS) = (u32x4){kh1[0], kh1[1], kh1[2], kh1[3]}; *(LAS u32x4*)(kw + TS + 16) = (u32x4){kh1[4], kh1[5], kh1[6], kh1[7]};
;     if (rg == 0) *(LAS f32x2*)(base + OFF_DL + (32 * w + 2 * cp) * 4) = (f32x2){all0, all1};
;     ...
;         HG_LOADE(gvA, qvA, 0); HG_LOADE(gvB, qvB, 1);
;         hgE<0>(lds, gvA, qvA, w, lane); HG_LOADE(gvA, qvA, 2);
;         HBAR();
;         for (int c = 0; c < NC; c += 2) {
;             if ((VAR & 8) == 0) hgE<1>(lds, gvB, qvB, w, lane); if ((VAR & 2) == 0) HG_LOADE(gvB, qvB, (c + 3 < NC ? c + 3 : NC - 1));
;             HBAR();
;             if ((VAR & 8) == 0) hgE<0>(lds, gvA, qvA, w, lane); if ((VAR & 2) == 0) HG_LOADE(gvA, qvA, (c + 4 < NC ? c + 4 : NC - 1));
	v_pk_mul_f32 v[48:49], v[58:59], v[28:29] op_sel_hi:[1,0]
	v_cvt_pk_bf16_f32 v29, v36, v37
	v_pk_mul_f32 v[36:37], v[38:39], v[64:65]
	v_cvt_pk_bf16_f32 v60, v60, v61
	v_cvt_pk_bf16_f32 v53, v48, v49
	v_cvt_pk_bf16_f32 v61, v46, v47
	v_pk_mul_f32 v[46:47], v[90:91], v[50:51]
	v_pk_mul_f32 v[40:41], v[70:71], v[40:41]
	v_cvt_pk_bf16_f32 v36, v36, v37
	v_add_u32_e32 v48, 0xf000, v89
	v_cvt_pk_bf16_f32 v31, v46, v47
	ds_write2_b32 v48, v29, v36 offset0:48 offset1:116
	v_mov_b32_e32 v36, v47
	v_mov_b32_e32 v37, v41
	v_lshlrev_b32_e32 v44, 16, v170
	v_and_b32_e32 v45, 0xffff0000, v170
	v_pk_add_f32 v[56:57], v[34:35], 1.0 op_sel_hi:[1,0] neg_lo:[1,0] neg_hi:[1,0]
	v_pk_mul_f32 v[36:37], v[36:37], v[30:31] op_sel_hi:[1,0]
	v_pk_mul_f32 v[34:35], v[38:39], v[34:35]
	v_cvt_pk_bf16_f32 v29, v40, v41
	v_add_u32_e32 v49, 0x5000, v159
	v_mov_b32_e32 v47, v40
	v_rcp_f32_e32 v38, v34
	v_rcp_f32_e32 v39, v35
	v_cvt_pk_bf16_f32 v62, v36, v37
	v_pk_mul_f32 v[36:37], v[34:35], v[44:45]
	v_pk_mul_f32 v[34:35], v[34:35], v[32:33]
	ds_write2_b32 v49, v31, v29 offset0:48 offset1:116
	v_pk_mul_f32 v[40:41], v[46:47], v[28:29] op_sel_hi:[1,0]
	v_cvt_pk_bf16_f32 v29, v36, v37
	v_rcp_f32_e32 v36, v34
	v_rcp_f32_e32 v37, v35
	v_lshlrev_b32_e32 v42, 16, v167
	v_and_b32_e32 v43, 0xffff0000, v167
	v_pk_mul_f32 v[34:35], v[34:35], v[42:43]
	v_pk_add_f32 v[32:33], v[32:33], 1.0 op_sel_hi:[1,0] neg_lo:[1,0] neg_hi:[1,0]
	v_pk_mul_f32 v[38:39], v[56:57], v[38:39]
	v_pk_mul_f32 v[32:33], v[32:33], v[36:37]
	v_cvt_pk_bf16_f32 v34, v34, v35
	v_cvt_pk_bf16_f32 v31, v38, v39
	ds_write2_b32 v48, v29, v34 offset0:184 offset1:252
	v_cvt_pk_bf16_f32 v29, v32, v33
	v_mov_b32_e32 v34, v39
	v_mov_b32_e32 v35, v33
	v_mov_b32_e32 v39, v32
	v_cvt_pk_bf16_f32 v23, v78, v79
	v_pk_mul_f32 v[34:35], v[34:35], v[30:31] op_sel_hi:[1,0]
	v_pk_mul_f32 v[32:33], v[38:39], v[28:29] op_sel_hi:[1,0]
	v_cvt_pk_bf16_f32 v18, v106, v107
	v_cvt_pk_bf16_f32 v19, v76, v77
	v_cvt_pk_bf16_f32 v54, v40, v41
	ds_write2_b32 v49, v31, v29 offset0:184 offset1:252
	v_cvt_pk_bf16_f32 v63, v34, v35
	v_cvt_pk_bf16_f32 v55, v32, v33
	ds_write_b128 v156, v[20:23]
	ds_write_b128 v156, v[52:55] offset:16
	ds_write_b128 v156, v[16:19] offset:144
	ds_write_b128 v156, v[60:63] offset:160
	s_and_saveexec_b64 s[14:15], s[6:7]
	v_mov_b32_e32 v29, v30
	v_add_u32_e32 v16, 0x1c600, v157
	ds_write_b64 v16, v[28:29]
	s_or_b64 exec, exec, s[14:15]
	s_add_i32 s16, s16, 2
	s_min_u32 s0, s16, 0x7c
	s_lshl_b32 s0, s0, 18
	s_add_i32 s48, s0, 0xc0000
	v_lshl_add_u64 v[30:31], v[24:25], 0, s[48:49]
	v_add_co_u32_e32 v22, vcc, 0x1000, v30
	v_lshl_add_u64 v[28:29], v[26:27], 0, s[48:49]
	s_nop 0
	v_addc_co_u32_e32 v23, vcc, 0, v31, vcc
	v_add_co_u32_e32 v32, vcc, 0x1000, v28
	s_waitcnt vmcnt(31)
	v_cvt_f32_f16_sdwa v21, v0 dst_sel:DWORD dst_unused:UNUSED_PAD src0_sel:WORD_1
	v_addc_co_u32_e32 v33, vcc, 0, v29, vcc
	v_add_co_u32_e32 v34, vcc, 0x2000, v30
	v_cvt_f32_f16_e32 v20, v0
	s_nop 0
	v_addc_co_u32_e32 v35, vcc, 0, v31, vcc
	v_add_co_u32_e32 v36, vcc, 0x2000, v28
	s_waitcnt vmcnt(29)
	v_cvt_f32_f16_sdwa v19, v1 dst_sel:DWORD dst_unused:UNUSED_PAD src0_sel:WORD_1
	v_addc_co_u32_e32 v37, vcc, 0, v29, vcc
	v_add_co_u32_e32 v38, vcc, 0x3000, v30
	v_cvt_f32_f16_e32 v18, v1
	s_nop 0
	v_addc_co_u32_e32 v39, vcc, 0, v31, vcc
	v_add_co_u32_e32 v40, vcc, 0x3000, v28
	s_waitcnt vmcnt(27)
	v_cvt_f32_f16_sdwa v1, v2 dst_sel:DWORD dst_unused:UNUSED_PAD src0_sel:WORD_1
	v_addc_co_u32_e32 v41, vcc, 0, v29, vcc
	global_load_dword v151, v[30:31], off
	global_load_dword v153, v[28:29], off
	global_load_dword v154, v[22:23], off
	global_load_dword v150, v[32:33], off
	global_load_dword v148, v[34:35], off
	global_load_dword v149, v[36:37], off
	global_load_dword v147, v[38:39], off
	global_load_dword v146, v[40:41], off
	v_add_co_u32_e32 v22, vcc, 0x4000, v30
	v_cvt_f32_f16_e32 v0, v2
	s_nop 0
	v_addc_co_u32_e32 v23, vcc, 0, v31, vcc
	v_add_co_u32_e32 v32, vcc, 0x4000, v28
	s_waitcnt vmcnt(33)
	v_cvt_f32_f16_sdwa v17, v3 dst_sel:DWORD dst_unused:UNUSED_PAD src0_sel:WORD_1
	v_addc_co_u32_e32 v33, vcc, 0, v29, vcc
	v_add_co_u32_e32 v34, vcc, 0x5000, v30
	v_cvt_f32_f16_e32 v16, v3
	s_nop 0
	v_addc_co_u32_e32 v35, vcc, 0, v31, vcc
	v_add_co_u32_e32 v36, vcc, 0x5000, v28
	s_waitcnt vmcnt(31)
	v_cvt_f32_f16_sdwa v3, v4 dst_sel:DWORD dst_unused:UNUSED_PAD src0_sel:WORD_1
	v_addc_co_u32_e32 v37, vcc, 0, v29, vcc
	v_add_co_u32_e32 v38, vcc, 0x6000, v30
	v_cvt_f32_f16_e32 v2, v4
	s_nop 0
	v_addc_co_u32_e32 v39, vcc, 0, v31, vcc
	v_add_co_u32_e32 v40, vcc, 0x6000, v28
	s_waitcnt vmcnt(25)
	v_cvt_f32_f16_sdwa v73, v7 dst_sel:DWORD dst_unused:UNUSED_PAD src0_sel:WORD_1
	v_addc_co_u32_e32 v41, vcc, 0, v29, vcc
	v_add_co_u32_e32 v42, vcc, 0x7000, v30
	v_cvt_f32_f16_e32 v72, v7
	s_nop 0
	v_addc_co_u32_e32 v43, vcc, 0, v31, vcc
	v_add_co_u32_e32 v44, vcc, 0x7000, v28
	s_waitcnt vmcnt(23)
	v_cvt_f32_f16_sdwa v63, v8 dst_sel:DWORD dst_unused:UNUSED_PAD src0_sel:WORD_1
	v_addc_co_u32_e32 v45, vcc, 0, v29, vcc
	global_load_dword v164, v[22:23], off
	global_load_dword v163, v[32:33], off
	global_load_dword v162, v[34:35], off
	global_load_dword v161, v[36:37], off
	global_load_dword v158, v[38:39], off
	global_load_dword v160, v[40:41], off
	global_load_dword v155, v[42:43], off
	global_load_dword v152, v[44:45], off
	v_add_co_u32_e32 v32, vcc, 0x8000, v30
	v_cvt_f32_f16_sdwa v23, v5 dst_sel:DWORD dst_unused:UNUSED_PAD src0_sel:WORD_1
	s_nop 0
	v_addc_co_u32_e32 v33, vcc, 0, v31, vcc
	v_add_co_u32_e32 v34, vcc, 0x8000, v28
	v_cvt_f32_f16_e32 v22, v5
	s_nop 0
	v_addc_co_u32_e32 v35, vcc, 0, v29, vcc
	v_add_co_u32_e32 v36, vcc, 0x9000, v30
	v_cvt_f32_f16_e32 v62, v8
	s_nop 0
	v_addc_co_u32_e32 v37, vcc, 0, v31, vcc
	v_add_co_u32_e32 v38, vcc, 0x9000, v28
	s_waitcnt vmcnt(29)
; __device__ __forceinline__ float bf_lo(unsigned w) { return __uint_as_float(w << 16); }
; __device__ __forceinline__ float bf_hi(unsigned w) { return __uint_as_float(w & 0xffff0000u); }
; #define LAS __attribute__((address_space(3)))
; #define HBAR() do { asm volatile("s_waitcnt lgkmcnt(0)" ::: "memory"); __builtin_amdgcn_s_barrier(); asm volatile("" ::: "memory"); } while (0)
; #define HG_LOADE(GV, QV, c_) do { const size_t adv_ = (size_t)(c_) * 64 * DM; _Pragma("unroll") for (int j = 0; j < 16; ++j) { GV[j] = *(const unsigned*)(gp + adv_ + (size_t)j * DM); QV[j] = *(const unsigned*)(qp + adv_ + (size_t)j * DM); } } while (0)
; template <int SET> __device__ __forceinline__ void hgE(LAS unsigned char* lds, const unsigned (&gh)[16], const unsigned (&qv)[16], int w, int lane) {
;     ...
;     f32x2 gv[16];
; #pragma unroll
;     for (int j = 0; j < 16; ++j) { const f16x2_t t = __builtin_bit_cast(f16x2_t, gh[j]); gv[j] = (f32x2){(float)t.x, (float)t.y}; }
;     const int cp = lane & 15, rg = lane >> 4;
;     float run0 = 1.f, run1 = 1.f;
; #pragma unroll
;     for (int j = 0; j < 16; ++j) { run0 *= gv[j].x; run1 *= gv[j].y; }
;     float i0 = run0, i1 = run1;
;     { const float a0 = __shfl_up(i0, 16), a1 = __shfl_up(i1, 16); if (rg >= 1) { i0 *= a0; i1 *= a1; } }
;     { const float a0 = __shfl_up(i0, 32), a1 = __shfl_up(i1, 32); if (rg >= 2) { i0 *= a0; i1 *= a1; } }
;     float pre0 = __shfl_up(i0, 16), pre1 = __shfl_up(i1, 16); if (rg == 0) { pre0 = 1.f; pre1 = 1.f; }
;     const float all0 = __shfl(i0, cp + 48), all1 = __shfl(i1, cp + 48);
;     unsigned kh0[8], kh1[8]; float kp0 = 0.f, kp1 = 0.f, ea = pre0, eb = pre1;
;     LAS unsigned char* qw = base + OFF_Q + (16 * rg) * QS + (32 * w + 2 * cp) * 2;
; #pragma unroll
;     for (int j = 0; j < 16; ++j) {
;         ea *= gv[j].x; eb *= gv[j].y;
;         const float qa = bf_lo(qv[j]) * ea, qb = bf_hi(qv[j]) * eb;
;         const float ka = (1.f - gv[j].x) * __builtin_amdgcn_rcpf(ea), kb = (1.f - gv[j].y) * __builtin_amdgcn_rcpf(eb);
;     ...
;             if ((VAR & 8) == 0) hgE<1>(lds, gvB, qvB, w, lane); if ((VAR & 2) == 0) HG_LOADE(gvB, qvB, (c + 3 < NC ? c + 3 : NC - 1));
;             HBAR();
;             if ((VAR & 8) == 0) hgE<0>(lds, gvA, qvA, w, lane); if ((VAR & 2) == 0) HG_LOADE(gvA, qvA, (c + 4 < NC ? c + 4 : NC - 1));
;             HBAR();
	v_cvt_f32_f16_sdwa v61, v9 dst_sel:DWORD dst_unused:UNUSED_PAD src0_sel:WORD_1
	v_addc_co_u32_e32 v39, vcc, 0, v29, vcc
	v_add_co_u32_e32 v40, vcc, 0xa000, v30
	v_cvt_f32_f16_e32 v60, v9
	s_nop 0
	v_addc_co_u32_e32 v41, vcc, 0, v31, vcc
	v_add_co_u32_e32 v4, vcc, 0xa000, v28
	s_waitcnt vmcnt(27)
	v_cvt_f32_f16_sdwa v49, v10 dst_sel:DWORD dst_unused:UNUSED_PAD src0_sel:WORD_1
	v_addc_co_u32_e32 v5, vcc, 0, v29, vcc
	v_add_co_u32_e32 v42, vcc, 0xb000, v30
	v_cvt_f32_f16_e32 v48, v10
	s_nop 0
	v_addc_co_u32_e32 v43, vcc, 0, v31, vcc
	v_add_co_u32_e32 v44, vcc, 0xb000, v28
	s_waitcnt vmcnt(25)
	v_cvt_f32_f16_sdwa v47, v11 dst_sel:DWORD dst_unused:UNUSED_PAD src0_sel:WORD_1
	v_addc_co_u32_e32 v45, vcc, 0, v29, vcc
	global_load_dword v175, v[32:33], off
	global_load_dword v174, v[34:35], off
	global_load_dword v173, v[36:37], off
	global_load_dword v172, v[38:39], off
	global_load_dword v168, v[40:41], off
	global_load_dword v169, v[4:5], off
	global_load_dword v166, v[42:43], off
	global_load_dword v165, v[44:45], off
	v_add_co_u32_e32 v4, vcc, s66, v30
	v_cvt_f32_f16_e32 v46, v11
	s_nop 0
	v_addc_co_u32_e32 v5, vcc, 0, v31, vcc
	v_add_co_u32_e32 v32, vcc, s66, v28
	s_waitcnt vmcnt(25)
	v_cvt_f32_f16_sdwa v9, v15 dst_sel:DWORD dst_unused:UNUSED_PAD src0_sel:WORD_1
	v_addc_co_u32_e32 v33, vcc, 0, v29, vcc
	v_add_co_u32_e32 v34, vcc, 0xd000, v30
	v_cvt_f32_f16_e32 v8, v15
	s_nop 0
	v_addc_co_u32_e32 v35, vcc, 0, v31, vcc
	v_add_co_u32_e32 v36, vcc, 0xd000, v28
	v_lshlrev_b32_e32 v110, 16, v96
	s_nop 0
	v_addc_co_u32_e32 v37, vcc, 0, v29, vcc
	v_add_co_u32_e32 v38, vcc, 0xe000, v30
	v_and_b32_e32 v111, 0xffff0000, v96
	s_nop 0
	v_addc_co_u32_e32 v39, vcc, 0, v31, vcc
	v_add_co_u32_e32 v40, vcc, 0xe000, v28
	v_pk_add_f32 v[108:109], v[20:21], 1.0 op_sel_hi:[1,0] neg_lo:[1,0] neg_hi:[1,0]
	s_nop 0
	v_addc_co_u32_e32 v41, vcc, 0, v29, vcc
	v_add_co_u32_e32 v30, vcc, 0xf000, v30
	v_pk_add_f32 v[112:113], v[18:19], 1.0 op_sel_hi:[1,0] neg_lo:[1,0] neg_hi:[1,0]
	s_nop 0
	v_addc_co_u32_e32 v31, vcc, 0, v31, vcc
	v_add_co_u32_e32 v28, vcc, 0xf000, v28
	v_lshlrev_b32_e32 v106, 16, v94
	s_nop 0
	v_addc_co_u32_e32 v29, vcc, 0, v29, vcc
	global_load_dword v178, v[4:5], off
	global_load_dword v180, v[32:33], off
	global_load_dword v179, v[34:35], off
	global_load_dword v171, v[36:37], off
	global_load_dword v177, v[38:39], off
	global_load_dword v170, v[40:41], off
	global_load_dword v176, v[30:31], off
	global_load_dword v167, v[28:29], off
	v_pk_mul_f32 v[28:29], v[20:21], v[18:19]
	v_cvt_f32_f16_sdwa v41, v6 dst_sel:DWORD dst_unused:UNUSED_PAD src0_sel:WORD_1
	v_cvt_f32_f16_e32 v40, v6
	v_pk_mul_f32 v[28:29], v[28:29], v[0:1]
	v_cvt_f32_f16_sdwa v33, v12 dst_sel:DWORD dst_unused:UNUSED_PAD src0_sel:WORD_1
	v_pk_mul_f32 v[28:29], v[28:29], v[16:17]
	v_cvt_f32_f16_e32 v32, v12
	v_pk_mul_f32 v[28:29], v[28:29], v[2:3]
	s_waitcnt vmcnt(32)
	v_cvt_f32_f16_sdwa v31, v13 dst_sel:DWORD dst_unused:UNUSED_PAD src0_sel:WORD_1
	v_pk_mul_f32 v[28:29], v[28:29], v[22:23]
	v_cvt_f32_f16_e32 v30, v13
	v_pk_mul_f32 v[28:29], v[28:29], v[40:41]
	v_cvt_f32_f16_sdwa v13, v14 dst_sel:DWORD dst_unused:UNUSED_PAD src0_sel:WORD_1
	v_pk_mul_f32 v[6:7], v[28:29], v[72:73]
	v_cvt_f32_f16_e32 v12, v14
	v_pk_mul_f32 v[6:7], v[6:7], v[62:63]
	v_lshlrev_b32_e32 v4, 16, v97
	v_pk_mul_f32 v[6:7], v[6:7], v[60:61]
	v_and_b32_e32 v5, 0xffff0000, v97
	v_pk_mul_f32 v[6:7], v[6:7], v[48:49]
	s_waitcnt lgkmcnt(0)
	s_barrier
	v_pk_mul_f32 v[6:7], v[6:7], v[46:47]
	v_and_b32_e32 v107, 0xffff0000, v94
	v_pk_mul_f32 v[6:7], v[6:7], v[32:33]
	v_pk_add_f32 v[100:101], v[16:17], 1.0 op_sel_hi:[1,0] neg_lo:[1,0] neg_hi:[1,0]
	v_pk_mul_f32 v[6:7], v[6:7], v[30:31]
	v_pk_add_f32 v[104:105], v[0:1], 1.0 op_sel_hi:[1,0] neg_lo:[1,0] neg_hi:[1,0]
	v_pk_mul_f32 v[6:7], v[6:7], v[12:13]
	v_lshlrev_b32_e32 v102, 16, v95
	v_pk_mul_f32 v[6:7], v[6:7], v[8:9]
	v_mov_b32_e32 v216, v6
	v_mov_b32_e32 v217, v7
	v_mov_b32_e32 v218, v6
	v_mov_b32_e32 v219, v7
	s_nop 1
	v_permlane16_swap_b32_e32 v216, v218
	v_permlane16_swap_b32_e32 v217, v219
	v_pk_mul_f32 v[220:221], v[216:217], v[218:219]
	v_mov_b32_e32 v228, 1.0
	v_mov_b32_e32 v229, 1.0
	v_mov_b32_e32 v222, v220
	v_mov_b32_e32 v223, v221
	s_nop 1
	v_permlane32_swap_b32_e32 v222, v220
	v_permlane32_swap_b32_e32 v223, v221
	v_permlane16_swap_b32_e32 v228, v216
	v_permlane16_swap_b32_e32 v229, v217
	v_pk_mul_f32 v[224:225], v[222:223], v[220:221]
	v_cndmask_b32_e64 v226, 1.0, v222, s[10:11]
	v_cndmask_b32_e64 v227, 1.0, v223, s[10:11]
	v_pk_mul_f32 v[6:7], v[226:227], v[228:229]
	v_mov_b32_e32 v10, v224
	v_and_b32_e32 v103, 0xffff0000, v95
	v_lshlrev_b32_e32 v98, 16, v99
	v_and_b32_e32 v99, 0xffff0000, v99
	v_pk_add_f32 v[96:97], v[2:3], 1.0 op_sel_hi:[1,0] neg_lo:[1,0] neg_hi:[1,0]
	v_lshlrev_b32_e32 v94, 16, v183
	v_and_b32_e32 v95, 0xffff0000, v183
	v_pk_add_f32 v[92:93], v[22:23], 1.0 op_sel_hi:[1,0] neg_lo:[1,0] neg_hi:[1,0]
	v_lshlrev_b32_e32 v58, 16, v182
	v_pk_mul_f32 v[6:7], v[6:7], v[20:21]
	v_mov_b32_e32 v14, v225
	v_rcp_f32_e32 v20, v6
	v_rcp_f32_e32 v21, v7
	v_pk_mul_f32 v[110:111], v[6:7], v[110:111]
	v_pk_mul_f32 v[6:7], v[6:7], v[18:19]
	v_cvt_pk_bf16_f32 v11, v110, v111
	v_rcp_f32_e32 v18, v6
	v_rcp_f32_e32 v19, v7
	v_pk_mul_f32 v[4:5], v[6:7], v[4:5]
	v_pk_mul_f32 v[20:21], v[108:109], v[20:21]
	v_cvt_pk_bf16_f32 v4, v4, v5
	v_pk_mul_f32 v[18:19], v[112:113], v[18:19]
	v_cvt_pk_bf16_f32 v15, v20, v21
	ds_write2_b32 v89, v11, v4 offset1:68
	v_cvt_pk_bf16_f32 v4, v18, v19
	ds_write2_b32 v138, v15, v4 offset1:68
	v_mov_b32_e32 v4, v21
	v_mov_b32_e32 v5, v19
	v_mov_b32_e32 v21, v18
	v_pk_mul_f32 v[6:7], v[6:7], v[0:1]
	s_waitcnt lgkmcnt(2)
; __device__ __forceinline__ unsigned cvtpk_s(float lo, float hi) { f32x2_t v = {lo, hi}; bf16x2_t b = __builtin_convertvector(v, bf16x2_t); return __builtin_bit_cast(unsigned, b); }
; __device__ __forceinline__ float bf_lo(unsigned w) { return __uint_as_float(w << 16); }
; __device__ __forceinline__ float bf_hi(unsigned w) { return __uint_as_float(w & 0xffff0000u); }
; #define LAS __attribute__((address_space(3)))
; template <int SET> __device__ __forceinline__ void hgE(LAS unsigned char* lds, const unsigned (&gh)[16], const unsigned (&qv)[16], int w, int lane) {
;     ...
; #pragma unroll
;     for (int j = 0; j < 16; ++j) {
;         ea *= gv[j].x; eb *= gv[j].y;
;         const float qa = bf_lo(qv[j]) * ea, qb = bf_hi(qv[j]) * eb;
;         const float ka = (1.f - gv[j].x) * __builtin_amdgcn_rcpf(ea), kb = (1.f - gv[j].y) * __builtin_amdgcn_rcpf(eb);
;         *(LAS unsigned*)(qw + j * QS) = cvtpk_s(qa, qb);
;         *(LAS unsigned*)(qw + (OFF_K - OFF_Q) + j * QS) = cvtpk_s(ka, kb);
;         const float ha = ka * all0, hb = kb * all1;
;         if (j & 1) { kh0[j >> 1] = cvtpk_s(kp0, ha); kh1[j >> 1] = cvtpk_s(kp1, hb); } else { kp0 = ha; kp1 = hb; }
;     }
	v_pk_mul_f32 v[108:109], v[4:5], v[14:15] op_sel_hi:[1,0]
	v_pk_mul_f32 v[4:5], v[20:21], v[10:11] op_sel_hi:[1,0]
	v_rcp_f32_e32 v18, v6
	v_rcp_f32_e32 v19, v7
	v_pk_mul_f32 v[20:21], v[6:7], v[106:107]
	v_pk_mul_f32 v[6:7], v[6:7], v[16:17]
	v_cvt_pk_bf16_f32 v1, v20, v21
	v_rcp_f32_e32 v16, v6
	v_rcp_f32_e32 v17, v7
	v_pk_mul_f32 v[18:19], v[104:105], v[18:19]
	v_pk_mul_f32 v[20:21], v[6:7], v[102:103]
	v_cvt_pk_bf16_f32 v4, v4, v5
	v_pk_mul_f32 v[16:17], v[100:101], v[16:17]
	v_cvt_pk_bf16_f32 v5, v18, v19
	v_cvt_pk_bf16_f32 v11, v20, v21
	v_mov_b32_e32 v20, v19
	v_mov_b32_e32 v19, v16
	ds_write2_b32 v89, v1, v11 offset0:136 offset1:204
	v_cvt_pk_bf16_f32 v1, v16, v17
	v_mov_b32_e32 v21, v17
	v_pk_mul_f32 v[16:17], v[18:19], v[10:11] op_sel_hi:[1,0]
	v_pk_mul_f32 v[2:3], v[6:7], v[2:3]
	ds_write2_b32 v138, v5, v1 offset0:136 offset1:204
	v_rcp_f32_e32 v6, v2
	v_rcp_f32_e32 v7, v3
	v_cvt_pk_bf16_f32 v5, v16, v17
	v_pk_mul_f32 v[16:17], v[2:3], v[98:99]
	v_pk_mul_f32 v[2:3], v[2:3], v[22:23]
	v_cvt_pk_bf16_f32 v11, v16, v17
	v_rcp_f32_e32 v18, v2
	v_rcp_f32_e32 v19, v3
	v_pk_mul_f32 v[16:17], v[2:3], v[94:95]
	v_pk_mul_f32 v[6:7], v[96:97], v[6:7]
	v_cvt_pk_bf16_f32 v16, v16, v17
	v_pk_mul_f32 v[18:19], v[92:93], v[18:19]
	v_pk_mul_f32 v[20:21], v[20:21], v[14:15] op_sel_hi:[1,0]
	v_cvt_pk_bf16_f32 v15, v6, v7
	ds_write2_b32 v139, v11, v16 offset0:16 offset1:84
	v_mov_b32_e32 v16, v7
	v_mov_b32_e32 v17, v19
	v_and_b32_e32 v59, 0xffff0000, v182
	v_cvt_pk_bf16_f32 v11, v18, v19
	v_pk_mul_f32 v[16:17], v[16:17], v[14:15] op_sel_hi:[1,0]
	v_mov_b32_e32 v7, v18
	v_pk_mul_f32 v[18:19], v[2:3], v[40:41]
	v_cvt_pk_bf16_f32 v1, v20, v21
	v_rcp_f32_e32 v20, v18
	v_rcp_f32_e32 v21, v19
	v_cvt_pk_bf16_f32 v2, v16, v17
	v_pk_mul_f32 v[16:17], v[18:19], v[58:59]
	v_pk_mul_f32 v[18:19], v[18:19], v[72:73]
	v_lshlrev_b32_e32 v64, 16, v181
	v_rcp_f32_e32 v22, v18
	v_rcp_f32_e32 v23, v19
	v_and_b32_e32 v65, 0xffff0000, v181
	v_pk_add_f32 v[76:77], v[40:41], 1.0 op_sel_hi:[1,0] neg_lo:[1,0] neg_hi:[1,0]
	v_pk_add_f32 v[78:79], v[72:73], 1.0 op_sel_hi:[1,0] neg_lo:[1,0] neg_hi:[1,0]
	v_cvt_pk_bf16_f32 v3, v16, v17
	v_pk_mul_f32 v[16:17], v[18:19], v[64:65]
	ds_write2_b32 v140, v15, v11 offset0:16 offset1:84
	v_pk_mul_f32 v[6:7], v[6:7], v[10:11] op_sel_hi:[1,0]
	v_pk_mul_f32 v[20:21], v[76:77], v[20:21]
	v_pk_mul_f32 v[22:23], v[78:79], v[22:23]
	v_cvt_pk_bf16_f32 v11, v16, v17
	v_pk_mul_f32 v[18:19], v[18:19], v[62:63]
	v_cvt_pk_bf16_f32 v6, v6, v7
	v_cvt_pk_bf16_f32 v7, v20, v21
	ds_write2_b32 v139, v3, v11 offset0:152 offset1:220
	v_cvt_pk_bf16_f32 v3, v22, v23
	v_mov_b32_e32 v16, v21
	v_mov_b32_e32 v17, v23
	v_mov_b32_e32 v21, v22
	v_rcp_f32_e32 v22, v18
	v_rcp_f32_e32 v23, v19
	v_lshlrev_b32_e32 v52, 16, v187
	v_and_b32_e32 v53, 0xffff0000, v187
	v_pk_mul_f32 v[16:17], v[16:17], v[14:15] op_sel_hi:[1,0]
	v_pk_add_f32 v[68:69], v[62:63], 1.0 op_sel_hi:[1,0] neg_lo:[1,0] neg_hi:[1,0]
	ds_write2_b32 v140, v7, v3 offset0:152 offset1:220
	v_pk_mul_f32 v[20:21], v[20:21], v[10:11] op_sel_hi:[1,0]
	v_cvt_pk_bf16_f32 v3, v16, v17
	v_pk_mul_f32 v[16:17], v[18:19], v[52:53]
	v_pk_mul_f32 v[18:19], v[18:19], v[60:61]
	v_cvt_pk_bf16_f32 v7, v20, v21
	v_pk_mul_f32 v[20:21], v[68:69], v[22:23]
	v_rcp_f32_e32 v22, v18
	v_rcp_f32_e32 v23, v19
	v_lshlrev_b32_e32 v50, 16, v186
	v_and_b32_e32 v51, 0xffff0000, v186
	v_pk_add_f32 v[70:71], v[60:61], 1.0 op_sel_hi:[1,0] neg_lo:[1,0] neg_hi:[1,0]
	v_cvt_pk_bf16_f32 v11, v16, v17
	v_pk_mul_f32 v[16:17], v[18:19], v[50:51]
	v_pk_mul_f32 v[22:23], v[70:71], v[22:23]
	v_cvt_pk_bf16_f32 v16, v16, v17
	v_lshlrev_b32_e32 v38, 16, v185
	v_and_b32_e32 v39, 0xffff0000, v185
	v_cvt_pk_bf16_f32 v15, v20, v21
	ds_write2_b32 v141, v11, v16 offset0:32 offset1:100
	v_mov_b32_e32 v16, v21
	v_mov_b32_e32 v17, v23
	v_pk_mul_f32 v[18:19], v[18:19], v[48:49]
	v_cvt_pk_bf16_f32 v11, v22, v23
	v_pk_mul_f32 v[40:41], v[16:17], v[14:15] op_sel_hi:[1,0]
; __device__ __forceinline__ unsigned cvtpk_s(float lo, float hi) { f32x2_t v = {lo, hi}; bf16x2_t b = __builtin_convertvector(v, bf16x2_t); return __builtin_bit_cast(unsigned, b); }
; __device__ __forceinline__ float bf_lo(unsigned w) { return __uint_as_float(w << 16); }
; __device__ __forceinline__ float bf_hi(unsigned w) { return __uint_as_float(w & 0xffff0000u); }
; #define LAS __attribute__((address_space(3)))
; template <int SET> __device__ __forceinline__ void hgE(LAS unsigned char* lds, const unsigned (&gh)[16], const unsigned (&qv)[16], int w, int lane) {
;     ...
; #pragma unroll
;     for (int j = 0; j < 16; ++j) {
;         ea *= gv[j].x; eb *= gv[j].y;
;         const float qa = bf_lo(qv[j]) * ea, qb = bf_hi(qv[j]) * eb;
;         const float ka = (1.f - gv[j].x) * __builtin_amdgcn_rcpf(ea), kb = (1.f - gv[j].y) * __builtin_amdgcn_rcpf(eb);
;         *(LAS unsigned*)(qw + j * QS) = cvtpk_s(qa, qb);
;         *(LAS unsigned*)(qw + (OFF_K - OFF_Q) + j * QS) = cvtpk_s(ka, kb);
;         const float ha = ka * all0, hb = kb * all1;
;         if (j & 1) { kh0[j >> 1] = cvtpk_s(kp0, ha); kh1[j >> 1] = cvtpk_s(kp1, hb); } else { kp0 = ha; kp1 = hb; }
;     }
;     LAS unsigned char* kw = base + OFF_KT + (32 * w + 2 * cp) * TS + rg * 32;
;     *(LAS u32x4*)(kw) = (u32x4){kh0[0], kh0[1], kh0[2], kh0[3]}; *(LAS u32x4*)(kw + 16) = (u32x4){kh0[4], kh0[5], kh0[6], kh0[7]};
;     *(LAS u32x4*)(kw + TS) = (u32x4){kh1[0], kh1[1], kh1[2], kh1[3]}; *(LAS u32x4*)(kw + TS + 16) = (u32x4){kh1[4], kh1[5], kh1[6], kh1[7]};
;     if (rg == 0) *(LAS f32x2*)(base + OFF_DL + (32 * w + 2 * cp) * 4) = (f32x2){all0, all1};
	v_mov_b32_e32 v21, v22
	v_rcp_f32_e32 v22, v18
	v_rcp_f32_e32 v23, v19
	v_pk_mul_f32 v[38:39], v[18:19], v[38:39]
	v_pk_mul_f32 v[18:19], v[18:19], v[46:47]
	v_pk_mul_f32 v[16:17], v[20:21], v[10:11] op_sel_hi:[1,0]
	v_cvt_pk_bf16_f32 v20, v40, v41
	v_rcp_f32_e32 v40, v18
	v_rcp_f32_e32 v41, v19
	v_lshlrev_b32_e32 v36, 16, v184
	v_and_b32_e32 v37, 0xffff0000, v184
	v_pk_add_f32 v[56:57], v[48:49], 1.0 op_sel_hi:[1,0] neg_lo:[1,0] neg_hi:[1,0]
	v_pk_add_f32 v[42:43], v[46:47], 1.0 op_sel_hi:[1,0] neg_lo:[1,0] neg_hi:[1,0]
	v_pk_mul_f32 v[36:37], v[18:19], v[36:37]
	ds_write2_b32 v142, v15, v11 offset0:32 offset1:100
	v_cvt_pk_bf16_f32 v16, v16, v17
	v_pk_mul_f32 v[22:23], v[56:57], v[22:23]
	v_cvt_pk_bf16_f32 v11, v38, v39
	v_pk_mul_f32 v[38:39], v[42:43], v[40:41]
	v_cvt_pk_bf16_f32 v17, v36, v37
	v_cvt_pk_bf16_f32 v15, v22, v23
	ds_write2_b32 v141, v11, v17 offset0:168 offset1:236
	v_cvt_pk_bf16_f32 v11, v38, v39
	v_mov_b32_e32 v36, v23
	v_mov_b32_e32 v23, v38
	v_lshlrev_b32_e32 v28, 16, v191
	v_and_b32_e32 v29, 0xffff0000, v191
	v_pk_mul_f32 v[22:23], v[22:23], v[10:11] op_sel_hi:[1,0]
	v_pk_mul_f32 v[18:19], v[18:19], v[32:33]
	v_pk_add_f32 v[90:91], v[32:33], 1.0 op_sel_hi:[1,0] neg_lo:[1,0] neg_hi:[1,0]
	v_rcp_f32_e32 v32, v18
	v_rcp_f32_e32 v33, v19
	v_cvt_pk_bf16_f32 v17, v22, v23
	v_pk_mul_f32 v[22:23], v[18:19], v[28:29]
	v_pk_mul_f32 v[18:19], v[18:19], v[30:31]
	v_pk_add_f32 v[74:75], v[30:31], 1.0 op_sel_hi:[1,0] neg_lo:[1,0] neg_hi:[1,0]
	v_rcp_f32_e32 v30, v18
	v_rcp_f32_e32 v31, v19
	v_lshlrev_b32_e32 v66, 16, v190
	v_and_b32_e32 v67, 0xffff0000, v190
	ds_write2_b32 v142, v15, v11 offset0:168 offset1:236
	v_cvt_pk_bf16_f32 v11, v22, v23
	v_pk_mul_f32 v[22:23], v[18:19], v[66:67]
	v_mov_b32_e32 v37, v39
	v_pk_mul_f32 v[28:29], v[90:91], v[32:33]
	v_pk_mul_f32 v[30:31], v[74:75], v[30:31]
	v_cvt_pk_bf16_f32 v22, v22, v23
	v_pk_mul_f32 v[36:37], v[36:37], v[14:15] op_sel_hi:[1,0]
	v_cvt_pk_bf16_f32 v15, v28, v29
	ds_write2_b32 v143, v11, v22 offset0:48 offset1:116
	v_cvt_pk_bf16_f32 v11, v30, v31
	v_mov_b32_e32 v22, v29
	v_mov_b32_e32 v29, v30
	v_lshlrev_b32_e32 v44, 16, v189
	v_and_b32_e32 v45, 0xffff0000, v189
	v_pk_add_f32 v[54:55], v[12:13], 1.0 op_sel_hi:[1,0] neg_lo:[1,0] neg_hi:[1,0]
	v_pk_mul_f32 v[28:29], v[28:29], v[10:11] op_sel_hi:[1,0]
	v_pk_mul_f32 v[12:13], v[18:19], v[12:13]
	v_mov_b32_e32 v23, v31
	v_rcp_f32_e32 v30, v12
	v_rcp_f32_e32 v31, v13
	v_cvt_pk_bf16_f32 v18, v28, v29
	v_pk_mul_f32 v[28:29], v[12:13], v[44:45]
	v_pk_mul_f32 v[12:13], v[12:13], v[8:9]
	ds_write2_b32 v144, v15, v11 offset0:48 offset1:116
	v_cvt_pk_bf16_f32 v11, v28, v29
	v_rcp_f32_e32 v28, v12
	v_rcp_f32_e32 v29, v13
	v_lshlrev_b32_e32 v34, 16, v188
	v_and_b32_e32 v35, 0xffff0000, v188
	v_pk_mul_f32 v[12:13], v[12:13], v[34:35]
	v_pk_add_f32 v[8:9], v[8:9], 1.0 op_sel_hi:[1,0] neg_lo:[1,0] neg_hi:[1,0]
	v_pk_mul_f32 v[30:31], v[54:55], v[30:31]
	v_pk_mul_f32 v[8:9], v[8:9], v[28:29]
	v_cvt_pk_bf16_f32 v12, v12, v13
	v_pk_mul_f32 v[22:23], v[22:23], v[14:15] op_sel_hi:[1,0]
	v_cvt_pk_bf16_f32 v15, v30, v31
	ds_write2_b32 v143, v11, v12 offset0:184 offset1:252
	v_cvt_pk_bf16_f32 v11, v8, v9
	v_mov_b32_e32 v12, v31
	v_mov_b32_e32 v13, v9
	v_mov_b32_e32 v31, v8
	v_pk_mul_f32 v[12:13], v[12:13], v[14:15] op_sel_hi:[1,0]
	v_pk_mul_f32 v[8:9], v[30:31], v[10:11] op_sel_hi:[1,0]
	v_cvt_pk_bf16_f32 v0, v108, v109
	v_cvt_pk_bf16_f32 v21, v36, v37
	v_cvt_pk_bf16_f32 v22, v22, v23
	ds_write2_b32 v144, v15, v11 offset0:184 offset1:252
	v_cvt_pk_bf16_f32 v23, v12, v13
	v_cvt_pk_bf16_f32 v19, v8, v9
	ds_write_b128 v145, v[4:7] offset:34816
	ds_write_b128 v145, v[16:19] offset:34832
	ds_write_b128 v145, v[0:3] offset:34960
	ds_write_b128 v145, v[20:23] offset:34976
	s_and_saveexec_b64 s[14:15], s[6:7]
	s_cbranch_execz .LBB0_1187
	v_mov_b32_e32 v11, v14
	ds_write_b64 v157, v[10:11] offset:57856
	s_branch .LBB0_1187

; __device__ __forceinline__ int fresh_tid(int wave_s) { int l; asm volatile("v_mbcnt_lo_u32_b32 %0, -1, 0\n\tv_mbcnt_hi_u32_b32 %0, -1, %0" : "=v"(l)); return wave_s * 64 + l; }
; #define PG8_LAS __attribute__((address_space(3)))
;     __host__ __device__ bool next(int i, Unit& u) const {
;         const long L = (long)i * G + c; if (L >= nwg) return false;
;         int wgid = (int)L; { const int q = nwg / NXCD, r = nwg % NXCD, xcd = wgid % NXCD, off = wgid / NXCD; wgid = (xcd < r ? xcd * (q + 1) : r * (q + 1) + (xcd - r) * q) + off; }
;         const int nig = WGM * nN, gid = wgid / nig, fm = gid * WGM, gsz = (nM - fm) < WGM ? (nM - fm) : WGM;
;         u.pm = fm + ((wgid % nig) % gsz); u.pn = (wgid % nig) / gsz; return true;
;     }
; template <class Epi, class Sched, bool ALIGN_EPI = false, bool SP2 = false>
; __device__ __forceinline__ void gemm_phase(PG8_LAS unsigned char* lds, const Gemm g, const Sched& S, const Epi& E, int wave_s) {
;     const int tid = fresh_tid(wave_s), wid = __builtin_amdgcn_readfirstlane(tid >> 6), lane = tid & 63, wr = wid >> 2, wc = wid & 3, fr = lane & 15, fq = lane >> 4;
;     const int K = g.K, nt = K / BK;
;     unsigned voffA[2], voffB[2];
; #pragma unroll
;     for (int i = 0; i < 2; ++i) { int R, C; stage_rc(tid * 16 + i * 8192, R, C); const int Rb = Epi::PERM ? ((R & ~31) + perm32(R & 31)) : R;
;         voffA[i] = (unsigned)(R * K + C) * 2u; voffB[i] = (unsigned)(Rb * K + C) * 2u; }
.LBB0_1481:
	s_or_b64 exec, exec, s[2:3]
	v_readlane_b32 s0, v255, 1
	s_waitcnt lgkmcnt(0)
	s_barrier
	v_mbcnt_lo_u32_b32 v8, -1, 0
	v_mbcnt_hi_u32_b32 v8, -1, v8
	s_nop 0
	v_add_u32_e32 v0, s0, v8
	v_readlane_b32 s0, v255, 15
	v_readlane_b32 s1, v255, 16
	s_and_b64 vcc, exec, s[0:1]
	v_readfirstlane_b32 s8, v0
	s_cbranch_vccnz .LBB0_1505
	s_ashr_i32 s19, s18, 31
	s_lshr_b32 s0, s19, 29
	s_add_i32 s4, s18, s0
	s_and_b32 s0, s4, -8
	s_sub_i32 s3, s18, s0
	s_cmp_gt_i32 s3, -1
	s_cbranch_scc0 .LBB0_1484
	s_lshl_b32 s2, s3, 7
	s_ashr_i32 s0, s4, 3
	s_cbranch_execz .LBB0_1485
	s_branch .LBB0_1486
